# gate phase: batched skinny-GEMM loads + single descending log-sigmoid pass (suffix sum); index loop v3; attn q in regs
# speedup vs baseline: 1.0273x; 1.0145x over previous
.LBB0_101:
	s_ashr_i32 s38, s41, 1
	s_lshl_b32 s24, s41, 5
	s_lshl_b32 s25, s38, 6
	s_and_b32 s39, s25, 0xfc0
	s_and_b32 s24, s24, 0xfffff000
	s_or_b32 s28, s39, s24
	v_or_b32_e32 v0, s28, v44
	v_ashrrev_i32_e32 v1, 31, v0
	v_lshlrev_b64 v[0:1], 12, v[0:1]
	s_barrier
	v_lshl_add_u64 v[12:13], v[4:5], 0, v[0:1]
	s_mov_b32 s4, 0x10000
	s_mov_b32 s24, 0x30000
	v_add_co_u32_e32 v0, vcc, 0x10000, v12
	s_nop 1
	v_addc_co_u32_e32 v1, vcc, 0, v13, vcc
	v_add_co_u32_e32 v2, vcc, 0x20000, v12
	s_nop 1
	v_addc_co_u32_e32 v3, vcc, 0, v13, vcc
	v_add_co_u32_e32 v10, vcc, 0x30000, v12
	s_nop 1
	v_addc_co_u32_e32 v11, vcc, 0, v13, vcc
	global_load_dwordx4 v[192:195], v[6:7], off
	global_load_dwordx4 v[76:79], v[12:13], off
	global_load_dwordx4 v[80:83], v[0:1], off
	global_load_dwordx4 v[84:87], v[2:3], off
	global_load_dwordx4 v[88:91], v[10:11], off
	global_load_dwordx4 v[196:199], v[6:7], off offset:64
	global_load_dwordx4 v[92:95], v[12:13], off offset:64
	global_load_dwordx4 v[96:99], v[0:1], off offset:64
	global_load_dwordx4 v[100:103], v[2:3], off offset:64
	global_load_dwordx4 v[104:107], v[10:11], off offset:64
	global_load_dwordx4 v[200:203], v[6:7], off offset:128
	global_load_dwordx4 v[108:111], v[12:13], off offset:128
	global_load_dwordx4 v[112:115], v[0:1], off offset:128
	global_load_dwordx4 v[116:119], v[2:3], off offset:128
	global_load_dwordx4 v[120:123], v[10:11], off offset:128
	global_load_dwordx4 v[204:207], v[6:7], off offset:192
	global_load_dwordx4 v[124:127], v[12:13], off offset:192
	global_load_dwordx4 v[128:131], v[0:1], off offset:192
	global_load_dwordx4 v[132:135], v[2:3], off offset:192
	global_load_dwordx4 v[136:139], v[10:11], off offset:192
	global_load_dwordx4 v[208:211], v[6:7], off offset:256
	global_load_dwordx4 v[140:143], v[12:13], off offset:256
	global_load_dwordx4 v[144:147], v[0:1], off offset:256
	global_load_dwordx4 v[148:151], v[2:3], off offset:256
	global_load_dwordx4 v[152:155], v[10:11], off offset:256
	global_load_dwordx4 v[212:215], v[6:7], off offset:320
	global_load_dwordx4 v[156:159], v[12:13], off offset:320
	global_load_dwordx4 v[160:163], v[0:1], off offset:320
	global_load_dwordx4 v[224:227], v[2:3], off offset:320
	global_load_dwordx4 v[228:231], v[10:11], off offset:320
	global_load_dwordx4 v[216:219], v[6:7], off offset:384
	global_load_dwordx4 v[232:235], v[12:13], off offset:384
	global_load_dwordx4 v[236:239], v[0:1], off offset:384
	global_load_dwordx4 v[240:243], v[2:3], off offset:384
	global_load_dwordx4 v[244:247], v[10:11], off offset:384
	global_load_dwordx4 v[220:223], v[6:7], off offset:448
	global_load_dwordx4 v[40:43], v[12:13], off offset:448
	global_load_dwordx4 v[48:51], v[0:1], off offset:448
	global_load_dwordx4 v[52:55], v[2:3], off offset:448
	global_load_dwordx4 v[56:59], v[10:11], off offset:448
	s_waitcnt vmcnt(35)
	v_mfma_f32_16x16x32_bf16 v[18:21], v[76:79], v[192:195], 0
	v_mfma_f32_16x16x32_bf16 v[22:25], v[80:83], v[192:195], 0
	v_mfma_f32_16x16x32_bf16 v[26:29], v[84:87], v[192:195], 0
	v_mfma_f32_16x16x32_bf16 v[14:17], v[88:91], v[192:195], 0
	s_waitcnt vmcnt(30)
	v_mfma_f32_16x16x32_bf16 v[18:21], v[92:95], v[196:199], v[18:21]
	v_mfma_f32_16x16x32_bf16 v[22:25], v[96:99], v[196:199], v[22:25]
	v_mfma_f32_16x16x32_bf16 v[26:29], v[100:103], v[196:199], v[26:29]
	v_mfma_f32_16x16x32_bf16 v[14:17], v[104:107], v[196:199], v[14:17]
	s_waitcnt vmcnt(25)
	v_mfma_f32_16x16x32_bf16 v[18:21], v[108:111], v[200:203], v[18:21]
	v_mfma_f32_16x16x32_bf16 v[22:25], v[112:115], v[200:203], v[22:25]
	v_mfma_f32_16x16x32_bf16 v[26:29], v[116:119], v[200:203], v[26:29]
	v_mfma_f32_16x16x32_bf16 v[14:17], v[120:123], v[200:203], v[14:17]
	s_waitcnt vmcnt(20)
	v_mfma_f32_16x16x32_bf16 v[18:21], v[124:127], v[204:207], v[18:21]
	v_mfma_f32_16x16x32_bf16 v[22:25], v[128:131], v[204:207], v[22:25]
	v_mfma_f32_16x16x32_bf16 v[26:29], v[132:135], v[204:207], v[26:29]
	v_mfma_f32_16x16x32_bf16 v[14:17], v[136:139], v[204:207], v[14:17]
	s_waitcnt vmcnt(15)
	v_mfma_f32_16x16x32_bf16 v[18:21], v[140:143], v[208:211], v[18:21]
	v_mfma_f32_16x16x32_bf16 v[22:25], v[144:147], v[208:211], v[22:25]
	v_mfma_f32_16x16x32_bf16 v[26:29], v[148:151], v[208:211], v[26:29]
	v_mfma_f32_16x16x32_bf16 v[14:17], v[152:155], v[208:211], v[14:17]
	s_waitcnt vmcnt(10)
	v_mfma_f32_16x16x32_bf16 v[18:21], v[156:159], v[212:215], v[18:21]
	v_mfma_f32_16x16x32_bf16 v[22:25], v[160:163], v[212:215], v[22:25]
	v_mfma_f32_16x16x32_bf16 v[26:29], v[224:227], v[212:215], v[26:29]
	v_mfma_f32_16x16x32_bf16 v[14:17], v[228:231], v[212:215], v[14:17]
	s_waitcnt vmcnt(5)
	v_mfma_f32_16x16x32_bf16 v[18:21], v[232:235], v[216:219], v[18:21]
	v_mfma_f32_16x16x32_bf16 v[22:25], v[236:239], v[216:219], v[22:25]
	v_mfma_f32_16x16x32_bf16 v[26:29], v[240:243], v[216:219], v[26:29]
	v_mfma_f32_16x16x32_bf16 v[14:17], v[244:247], v[216:219], v[14:17]
	s_waitcnt vmcnt(0)
	v_mfma_f32_16x16x32_bf16 v[18:21], v[40:43], v[220:223], v[18:21]
	v_mfma_f32_16x16x32_bf16 v[22:25], v[48:51], v[220:223], v[22:25]
	v_mfma_f32_16x16x32_bf16 v[26:29], v[52:55], v[220:223], v[26:29]
	v_mfma_f32_16x16x32_bf16 v[14:17], v[56:59], v[220:223], v[14:17]
	s_nop 7
	ds_write_b128 v45, v[18:21]
	ds_write_b128 v45, v[22:25] offset:1024
	ds_write_b128 v45, v[26:29] offset:2048
	ds_write_b128 v45, v[14:17] offset:3072
	s_waitcnt lgkmcnt(0)
	s_barrier
	s_and_saveexec_b64 s[24:25], s[36:37]
	s_cbranch_execz .LBB0_103
	ds_read_b128 v[0:3], v46
	ds_read_b128 v[10:13], v46 offset:4096
	s_ashr_i32 s29, s28, 31
	s_waitcnt lgkmcnt(0)
	v_pk_add_f32 v[12:13], v[2:3], v[12:13]
	v_pk_add_f32 v[10:11], v[0:1], v[10:11]
	ds_read_b128 v[0:3], v46 offset:8192
	s_waitcnt lgkmcnt(0)
	v_pk_add_f32 v[12:13], v[12:13], v[2:3]
	v_pk_add_f32 v[10:11], v[10:11], v[0:1]
	ds_read_b128 v[0:3], v46 offset:12288
	s_waitcnt lgkmcnt(0)
	v_pk_add_f32 v[12:13], v[12:13], v[2:3]
	v_pk_add_f32 v[10:11], v[10:11], v[0:1]
	ds_read_b128 v[0:3], v46 offset:16384
	s_waitcnt lgkmcnt(0)
	v_pk_add_f32 v[12:13], v[12:13], v[2:3]
	v_pk_add_f32 v[10:11], v[10:11], v[0:1]
	ds_read_b128 v[0:3], v46 offset:20480
	s_waitcnt lgkmcnt(0)
	v_pk_add_f32 v[12:13], v[12:13], v[2:3]
	v_pk_add_f32 v[10:11], v[10:11], v[0:1]
	ds_read_b128 v[0:3], v46 offset:24576
	s_waitcnt lgkmcnt(0)
	v_pk_add_f32 v[12:13], v[12:13], v[2:3]
	v_pk_add_f32 v[10:11], v[10:11], v[0:1]
	ds_read_b128 v[0:3], v46 offset:28672
	s_waitcnt lgkmcnt(0)
	v_pk_add_f32 v[10:11], v[10:11], v[0:1]
	v_lshl_add_u64 v[0:1], s[28:29], 2, v[8:9]
	v_pk_add_f32 v[12:13], v[12:13], v[2:3]
	global_load_dwordx4 v[0:3], v[0:1], off
	s_waitcnt vmcnt(0)
	v_mul_f32_e32 v0, v10, v0
	v_mul_f32_e32 v1, v11, v1
	v_add_u32_e32 v10, 0x8000, v47
	ds_write2_b32 v10, v0, v1 offset1:16
	v_mul_f32_e32 v0, v12, v2
	v_mul_f32_e32 v1, v13, v3
	ds_write2_b32 v10, v0, v1 offset0:32 offset1:48
.LBB0_103:
	s_or_b64 exec, exec, s[24:25]
	s_lshl_b32 s24, s41, 9
	s_and_b32 s24, s24, 0x200
	v_add_u32_e32 v10, s24, v33
	v_ashrrev_i32_e32 v11, 31, v10
	v_lshlrev_b64 v[0:1], 2, v[10:11]
	v_lshl_add_u64 v[2:3], s[0:1], 0, v[0:1]
	v_add_co_u32_e32 v14, vcc, 0x1000, v2
	s_movk_i32 s4, 0x4000
	s_nop 0
	v_addc_co_u32_e32 v15, vcc, 0, v3, vcc
	v_add_co_u32_e32 v16, vcc, 0x2000, v2
	s_waitcnt lgkmcnt(0)
	s_nop 0
	v_addc_co_u32_e32 v17, vcc, 0, v3, vcc
	v_add_co_u32_e32 v18, vcc, 0x3000, v2
	s_barrier
	s_nop 0
	v_addc_co_u32_e32 v19, vcc, 0, v3, vcc
	v_add_co_u32_e32 v20, vcc, s4, v2
	s_nop 1
	v_addc_co_u32_e32 v21, vcc, 0, v3, vcc
	v_add_co_u32_e32 v22, vcc, 0x5000, v2
	v_lshl_add_u64 v[0:1], s[2:3], 0, v[0:1]
	s_nop 0
	v_addc_co_u32_e32 v23, vcc, 0, v3, vcc
	v_add_co_u32_e32 v24, vcc, 0x6000, v2
	s_mov_b32 s24, 0
	s_nop 0
	v_addc_co_u32_e32 v25, vcc, 0, v3, vcc
	v_add_co_u32_e32 v26, vcc, 0x7000, v2
	s_nop 1
	v_addc_co_u32_e32 v27, vcc, 0, v3, vcc
	v_add_co_u32_e32 v28, vcc, 0x8000, v2
	global_load_dword v12, v[2:3], off
	s_nop 0
	global_load_dword v15, v[14:15], off
	s_nop 0
	global_load_dword v17, v[16:17], off
	s_nop 0
	global_load_dword v19, v[18:19], off
	s_nop 0
	global_load_dword v20, v[20:21], off
	s_nop 0
	global_load_dword v23, v[22:23], off
	s_nop 0
	global_load_dword v25, v[24:25], off
	s_nop 0
	global_load_dword v27, v[26:27], off
	v_addc_co_u32_e32 v29, vcc, 0, v3, vcc
	v_add_co_u32_e32 v30, vcc, 0x9000, v2
	s_nop 1
	v_addc_co_u32_e32 v31, vcc, 0, v3, vcc
	v_add_co_u32_e32 v34, vcc, 0xa000, v2
	s_nop 1
	v_addc_co_u32_e32 v35, vcc, 0, v3, vcc
	v_add_co_u32_e32 v40, vcc, 0xb000, v2
	s_nop 1
	v_addc_co_u32_e32 v41, vcc, 0, v3, vcc
	v_add_co_u32_e32 v42, vcc, 0xc000, v2
	s_nop 1
	v_addc_co_u32_e32 v43, vcc, 0, v3, vcc
	v_add_co_u32_e32 v48, vcc, 0xd000, v2
	s_nop 1
	v_addc_co_u32_e32 v49, vcc, 0, v3, vcc
	v_add_co_u32_e32 v50, vcc, 0xe000, v2
	s_nop 1
	v_addc_co_u32_e32 v51, vcc, 0, v3, vcc
	v_add_co_u32_e32 v2, vcc, 0xf000, v2
	s_nop 1
	v_addc_co_u32_e32 v3, vcc, 0, v3, vcc
	global_load_dword v13, v[28:29], off
	global_load_dword v14, v[30:31], off
	global_load_dword v16, v[34:35], off
	global_load_dword v18, v[40:41], off
	global_load_dword v21, v[42:43], off
	global_load_dword v22, v[48:49], off
	global_load_dword v24, v[50:51], off
	global_load_dword v26, v[2:3], off
	v_mov_b32_e32 v49, 0
	global_load_dword v48, v[0:1], off
	s_and_b32 s24, s31, 0x200
	v_add_u32_e32 v0, s24, v33
	s_and_b32 s24, s35, 0xfffff000
	s_or_b32 s24, s24, s39
	s_ashr_i32 s25, s24, 31
	s_lshl_b64 s[28:29], s[24:25], 1
	v_readlane_b32 s4, v252, 13
	v_ashrrev_i32_e32 v1, 31, v0
	s_add_u32 s28, s4, s28
	v_readlane_b32 s4, v252, 14
	v_lshlrev_b64 v[2:3], 15, v[0:1]
	s_addc_u32 s29, s4, s29
	s_mul_i32 s27, s24, 0x2200
	v_lshl_add_u64 v[28:29], s[28:29], 0, v[2:3]
	s_mul_hi_i32 s26, s24, 0x2200
	s_add_u32 s28, s90, s27
	s_addc_u32 s29, s91, s26
	s_add_u32 s26, s28, 0x1d386600
	s_addc_u32 s27, s29, 0
	v_lshlrev_b32_e32 v74, 1, v0
	s_lshl_b64 s[24:25], s[24:25], 2
	s_add_u32 s39, s90, s24
	v_readlane_b32 s4, v253, 4
	v_lshl_add_u64 v[30:31], v[0:1], 1, s[28:29]
	s_addc_u32 s42, s91, s25
	v_mov_b32_e32 v50, 0
	s_mov_b32 s43, 0
	v_readlane_b32 s5, v253, 5
	v_lshl_add_u64 v[28:29], v[28:29], 0, s[4:5]
	s_add_u32 s24, s39, s4
	s_addc_u32 s25, s42, s5
	s_add_u32 s28, s24, 0x38000000
	s_addc_u32 s29, s25, 0
	global_load_ushort v123, v74, s[26:27]
	s_sub_u32 s26, s26, 0x2200
	s_subb_u32 s27, s27, 0
	global_load_ushort v122, v74, s[26:27]
	s_sub_u32 s26, s26, 0x2200
	s_subb_u32 s27, s27, 0
	global_load_ushort v121, v74, s[26:27]
	s_sub_u32 s26, s26, 0x2200
	s_subb_u32 s27, s27, 0
	global_load_ushort v120, v74, s[26:27]
	s_sub_u32 s26, s26, 0x2200
	s_subb_u32 s27, s27, 0
	global_load_ushort v119, v74, s[26:27]
	s_sub_u32 s26, s26, 0x2200
	s_subb_u32 s27, s27, 0
	global_load_ushort v118, v74, s[26:27]
	s_sub_u32 s26, s26, 0x2200
	s_subb_u32 s27, s27, 0
	global_load_ushort v117, v74, s[26:27]
	s_sub_u32 s26, s26, 0x2200
	s_subb_u32 s27, s27, 0
	global_load_ushort v116, v74, s[26:27]
	s_sub_u32 s26, s26, 0x2200
	s_subb_u32 s27, s27, 0
	global_load_dwordx4 v[132:135], v32, s[28:29] offset:224
	global_load_dwordx4 v[136:139], v32, s[28:29] offset:240
	global_load_ushort v115, v74, s[26:27]
	s_sub_u32 s26, s26, 0x2200
	s_subb_u32 s27, s27, 0
	global_load_ushort v114, v74, s[26:27]
	s_sub_u32 s26, s26, 0x2200
	s_subb_u32 s27, s27, 0
	global_load_ushort v113, v74, s[26:27]
	s_sub_u32 s26, s26, 0x2200
	s_subb_u32 s27, s27, 0
	global_load_ushort v112, v74, s[26:27]
	s_sub_u32 s26, s26, 0x2200
	s_subb_u32 s27, s27, 0
	global_load_ushort v111, v74, s[26:27]
	s_sub_u32 s26, s26, 0x2200
	s_subb_u32 s27, s27, 0
	global_load_ushort v110, v74, s[26:27]
	s_sub_u32 s26, s26, 0x2200
	s_subb_u32 s27, s27, 0
	global_load_ushort v109, v74, s[26:27]
	s_sub_u32 s26, s26, 0x2200
	s_subb_u32 s27, s27, 0
	global_load_ushort v108, v74, s[26:27]
	s_sub_u32 s26, s26, 0x2200
	s_subb_u32 s27, s27, 0
	global_load_dwordx4 v[124:127], v32, s[28:29] offset:192
	global_load_dwordx4 v[128:131], v32, s[28:29] offset:208
	ds_read_b128 v[76:79], v32 offset:36800
	ds_read_b128 v[80:83], v32 offset:36816
	ds_read_b128 v[84:87], v32 offset:36832
	ds_read_b128 v[88:91], v32 offset:36848
	s_waitcnt vmcnt(10)
	ds_read_b128 v[92:95], v32 offset:36736
	ds_read_b128 v[96:99], v32 offset:36752
	ds_read_b128 v[100:103], v32 offset:36768
	ds_read_b128 v[104:107], v32 offset:36784
	s_waitcnt lgkmcnt(4)
	v_fma_f32 v152, v76, v12, v48
	v_fmac_f32_e32 v152, v77, v15
	v_fmac_f32_e32 v152, v78, v17
	v_fmac_f32_e32 v152, v79, v19
	v_fmac_f32_e32 v152, v80, v20
	v_fmac_f32_e32 v152, v81, v23
	v_fmac_f32_e32 v152, v82, v25
	v_fmac_f32_e32 v152, v83, v27
	v_fmac_f32_e32 v152, v84, v13
	v_fmac_f32_e32 v152, v85, v14
	v_fmac_f32_e32 v152, v86, v16
	v_fmac_f32_e32 v152, v87, v18
	v_fmac_f32_e32 v152, v88, v21
	v_fmac_f32_e32 v152, v89, v22
	v_fmac_f32_e32 v152, v90, v24
	v_fmac_f32_e32 v152, v91, v26
	v_min_f32_e32 v153, 0, v152
	v_mul_f32_e64 v154, |v152|, s52
	v_exp_f32_e32 v154, v154
	v_mul_f32_e32 v155, 0x3fb8aa3b, v49
	v_add_f32_e32 v154, 1.0, v154
	v_log_f32_e32 v154, v154
	v_exp_f32_e32 v155, v155
	v_lshlrev_b32_e32 v156, 16, v123
	v_fmac_f32_e32 v153, 0xbf317218, v154
	v_mul_f32_e32 v157, v155, v156
	v_mul_f32_e32 v147, v139, v157
	v_fmac_f32_e32 v49, 0x3d800000, v153
	ds_read_b128 v[76:79], v32 offset:36672
	ds_read_b128 v[80:83], v32 offset:36688
	ds_read_b128 v[84:87], v32 offset:36704
	ds_read_b128 v[88:91], v32 offset:36720
	s_waitcnt lgkmcnt(4)
	v_fma_f32 v152, v92, v12, v48
	v_fmac_f32_e32 v152, v93, v15
	v_fmac_f32_e32 v152, v94, v17
	v_fmac_f32_e32 v152, v95, v19
	v_fmac_f32_e32 v152, v96, v20
	v_fmac_f32_e32 v152, v97, v23
	v_fmac_f32_e32 v152, v98, v25
	v_fmac_f32_e32 v152, v99, v27
	v_fmac_f32_e32 v152, v100, v13
	v_fmac_f32_e32 v152, v101, v14
	v_fmac_f32_e32 v152, v102, v16
	v_fmac_f32_e32 v152, v103, v18
	v_fmac_f32_e32 v152, v104, v21
	v_fmac_f32_e32 v152, v105, v22
	v_fmac_f32_e32 v152, v106, v24
	v_fmac_f32_e32 v152, v107, v26
	v_min_f32_e32 v153, 0, v152
	v_mul_f32_e64 v154, |v152|, s52
	v_exp_f32_e32 v154, v154
	v_mul_f32_e32 v155, 0x3fb8aa3b, v49
	v_add_f32_e32 v154, 1.0, v154
	v_log_f32_e32 v154, v154
	v_exp_f32_e32 v155, v155
	v_lshlrev_b32_e32 v156, 16, v122
	v_fmac_f32_e32 v153, 0xbf317218, v154
	v_mul_f32_e32 v157, v155, v156
	v_mul_f32_e32 v146, v138, v157
	v_fmac_f32_e32 v49, 0x3d800000, v153
	ds_read_b128 v[92:95], v32 offset:36608
	ds_read_b128 v[96:99], v32 offset:36624
	ds_read_b128 v[100:103], v32 offset:36640
	ds_read_b128 v[104:107], v32 offset:36656
	s_waitcnt lgkmcnt(4)
	v_fma_f32 v152, v76, v12, v48
	v_fmac_f32_e32 v152, v77, v15
	v_fmac_f32_e32 v152, v78, v17
	v_fmac_f32_e32 v152, v79, v19
	v_fmac_f32_e32 v152, v80, v20
	v_fmac_f32_e32 v152, v81, v23
	v_fmac_f32_e32 v152, v82, v25
	v_fmac_f32_e32 v152, v83, v27
	v_fmac_f32_e32 v152, v84, v13
	v_fmac_f32_e32 v152, v85, v14
	v_fmac_f32_e32 v152, v86, v16
	v_fmac_f32_e32 v152, v87, v18
	v_fmac_f32_e32 v152, v88, v21
	v_fmac_f32_e32 v152, v89, v22
	v_fmac_f32_e32 v152, v90, v24
	v_fmac_f32_e32 v152, v91, v26
	v_min_f32_e32 v153, 0, v152
	v_mul_f32_e64 v154, |v152|, s52
	v_exp_f32_e32 v154, v154
	v_mul_f32_e32 v155, 0x3fb8aa3b, v49
	v_add_f32_e32 v154, 1.0, v154
	v_log_f32_e32 v154, v154
	v_exp_f32_e32 v155, v155
	v_lshlrev_b32_e32 v156, 16, v121
	v_fmac_f32_e32 v153, 0xbf317218, v154
	v_mul_f32_e32 v157, v155, v156
	v_mul_f32_e32 v145, v137, v157
	v_fmac_f32_e32 v49, 0x3d800000, v153
	ds_read_b128 v[76:79], v32 offset:36544
	ds_read_b128 v[80:83], v32 offset:36560
	ds_read_b128 v[84:87], v32 offset:36576
	ds_read_b128 v[88:91], v32 offset:36592
	s_waitcnt lgkmcnt(4)
	v_fma_f32 v152, v92, v12, v48
	v_fmac_f32_e32 v152, v93, v15
	v_fmac_f32_e32 v152, v94, v17
	v_fmac_f32_e32 v152, v95, v19
	v_fmac_f32_e32 v152, v96, v20
	v_fmac_f32_e32 v152, v97, v23
	v_fmac_f32_e32 v152, v98, v25
	v_fmac_f32_e32 v152, v99, v27
	v_fmac_f32_e32 v152, v100, v13
	v_fmac_f32_e32 v152, v101, v14
	v_fmac_f32_e32 v152, v102, v16
	v_fmac_f32_e32 v152, v103, v18
	v_fmac_f32_e32 v152, v104, v21
	v_fmac_f32_e32 v152, v105, v22
	v_fmac_f32_e32 v152, v106, v24
	v_fmac_f32_e32 v152, v107, v26
	v_min_f32_e32 v153, 0, v152
	v_mul_f32_e64 v154, |v152|, s52
	v_exp_f32_e32 v154, v154
	v_mul_f32_e32 v155, 0x3fb8aa3b, v49
	v_add_f32_e32 v154, 1.0, v154
	v_log_f32_e32 v154, v154
	v_exp_f32_e32 v155, v155
	v_lshlrev_b32_e32 v156, 16, v120
	v_fmac_f32_e32 v153, 0xbf317218, v154
	v_mul_f32_e32 v157, v155, v156
	v_mul_f32_e32 v144, v136, v157
	v_fmac_f32_e32 v49, 0x3d800000, v153
	ds_read_b128 v[92:95], v32 offset:36480
	ds_read_b128 v[96:99], v32 offset:36496
	ds_read_b128 v[100:103], v32 offset:36512
	ds_read_b128 v[104:107], v32 offset:36528
	s_waitcnt lgkmcnt(4)
	v_fma_f32 v152, v76, v12, v48
	v_fmac_f32_e32 v152, v77, v15
	v_fmac_f32_e32 v152, v78, v17
	v_fmac_f32_e32 v152, v79, v19
	v_fmac_f32_e32 v152, v80, v20
	v_fmac_f32_e32 v152, v81, v23
	v_fmac_f32_e32 v152, v82, v25
	v_fmac_f32_e32 v152, v83, v27
	v_fmac_f32_e32 v152, v84, v13
	v_fmac_f32_e32 v152, v85, v14
	v_fmac_f32_e32 v152, v86, v16
	v_fmac_f32_e32 v152, v87, v18
	v_fmac_f32_e32 v152, v88, v21
	v_fmac_f32_e32 v152, v89, v22
	v_fmac_f32_e32 v152, v90, v24
	v_fmac_f32_e32 v152, v91, v26
	v_min_f32_e32 v153, 0, v152
	v_mul_f32_e64 v154, |v152|, s52
	v_exp_f32_e32 v154, v154
	v_mul_f32_e32 v155, 0x3fb8aa3b, v49
	v_add_f32_e32 v154, 1.0, v154
	v_log_f32_e32 v154, v154
	v_exp_f32_e32 v155, v155
	v_lshlrev_b32_e32 v156, 16, v119
	v_fmac_f32_e32 v153, 0xbf317218, v154
	v_mul_f32_e32 v157, v155, v156
	v_mul_f32_e32 v143, v135, v157
	v_fmac_f32_e32 v49, 0x3d800000, v153
	ds_read_b128 v[76:79], v32 offset:36416
	ds_read_b128 v[80:83], v32 offset:36432
	ds_read_b128 v[84:87], v32 offset:36448
	ds_read_b128 v[88:91], v32 offset:36464
	s_waitcnt lgkmcnt(4)
	v_fma_f32 v152, v92, v12, v48
	v_fmac_f32_e32 v152, v93, v15
	v_fmac_f32_e32 v152, v94, v17
	v_fmac_f32_e32 v152, v95, v19
	v_fmac_f32_e32 v152, v96, v20
	v_fmac_f32_e32 v152, v97, v23
	v_fmac_f32_e32 v152, v98, v25
	v_fmac_f32_e32 v152, v99, v27
	v_fmac_f32_e32 v152, v100, v13
	v_fmac_f32_e32 v152, v101, v14
	v_fmac_f32_e32 v152, v102, v16
	v_fmac_f32_e32 v152, v103, v18
	v_fmac_f32_e32 v152, v104, v21
	v_fmac_f32_e32 v152, v105, v22
	v_fmac_f32_e32 v152, v106, v24
	v_fmac_f32_e32 v152, v107, v26
	v_min_f32_e32 v153, 0, v152
	v_mul_f32_e64 v154, |v152|, s52
	v_exp_f32_e32 v154, v154
	v_mul_f32_e32 v155, 0x3fb8aa3b, v49
	v_add_f32_e32 v154, 1.0, v154
	v_log_f32_e32 v154, v154
	v_exp_f32_e32 v155, v155
	v_lshlrev_b32_e32 v156, 16, v118
	v_fmac_f32_e32 v153, 0xbf317218, v154
	v_mul_f32_e32 v157, v155, v156
	v_mul_f32_e32 v142, v134, v157
	v_fmac_f32_e32 v49, 0x3d800000, v153
	ds_read_b128 v[92:95], v32 offset:36352
	ds_read_b128 v[96:99], v32 offset:36368
	ds_read_b128 v[100:103], v32 offset:36384
	ds_read_b128 v[104:107], v32 offset:36400
	s_waitcnt lgkmcnt(4)
	v_fma_f32 v152, v76, v12, v48
	v_fmac_f32_e32 v152, v77, v15
	v_fmac_f32_e32 v152, v78, v17
	v_fmac_f32_e32 v152, v79, v19
	v_fmac_f32_e32 v152, v80, v20
	v_fmac_f32_e32 v152, v81, v23
	v_fmac_f32_e32 v152, v82, v25
	v_fmac_f32_e32 v152, v83, v27
	v_fmac_f32_e32 v152, v84, v13
	v_fmac_f32_e32 v152, v85, v14
	v_fmac_f32_e32 v152, v86, v16
	v_fmac_f32_e32 v152, v87, v18
	v_fmac_f32_e32 v152, v88, v21
	v_fmac_f32_e32 v152, v89, v22
	v_fmac_f32_e32 v152, v90, v24
	v_fmac_f32_e32 v152, v91, v26
	v_min_f32_e32 v153, 0, v152
	v_mul_f32_e64 v154, |v152|, s52
	v_exp_f32_e32 v154, v154
	v_mul_f32_e32 v155, 0x3fb8aa3b, v49
	v_add_f32_e32 v154, 1.0, v154
	v_log_f32_e32 v154, v154
	v_exp_f32_e32 v155, v155
	v_lshlrev_b32_e32 v156, 16, v117
	v_fmac_f32_e32 v153, 0xbf317218, v154
	v_mul_f32_e32 v157, v155, v156
	v_mul_f32_e32 v141, v133, v157
	v_fmac_f32_e32 v49, 0x3d800000, v153
	ds_read_b128 v[76:79], v32 offset:36288
	ds_read_b128 v[80:83], v32 offset:36304
	ds_read_b128 v[84:87], v32 offset:36320
	ds_read_b128 v[88:91], v32 offset:36336
	s_waitcnt lgkmcnt(4)
	v_fma_f32 v152, v92, v12, v48
	v_fmac_f32_e32 v152, v93, v15
	v_fmac_f32_e32 v152, v94, v17
	v_fmac_f32_e32 v152, v95, v19
	v_fmac_f32_e32 v152, v96, v20
	v_fmac_f32_e32 v152, v97, v23
	v_fmac_f32_e32 v152, v98, v25
	v_fmac_f32_e32 v152, v99, v27
	v_fmac_f32_e32 v152, v100, v13
	v_fmac_f32_e32 v152, v101, v14
	v_fmac_f32_e32 v152, v102, v16
	v_fmac_f32_e32 v152, v103, v18
	v_fmac_f32_e32 v152, v104, v21
	v_fmac_f32_e32 v152, v105, v22
	v_fmac_f32_e32 v152, v106, v24
	v_fmac_f32_e32 v152, v107, v26
	v_min_f32_e32 v153, 0, v152
	v_mul_f32_e64 v154, |v152|, s52
	v_exp_f32_e32 v154, v154
	v_mul_f32_e32 v155, 0x3fb8aa3b, v49
	v_add_f32_e32 v154, 1.0, v154
	v_log_f32_e32 v154, v154
	v_exp_f32_e32 v155, v155
	v_lshlrev_b32_e32 v156, 16, v116
	v_fmac_f32_e32 v153, 0xbf317218, v154
	v_mul_f32_e32 v157, v155, v156
	v_mul_f32_e32 v140, v132, v157
	v_fmac_f32_e32 v49, 0x3d800000, v153
	v_cvt_pk_bf16_f32 v148, v140, v141
	v_cvt_pk_bf16_f32 v149, v142, v143
	v_cvt_pk_bf16_f32 v150, v144, v145
	v_cvt_pk_bf16_f32 v151, v146, v147
	global_store_dwordx4 v[28:29], v[148:151], off offset:112
	global_load_ushort v123, v74, s[26:27]
	s_sub_u32 s26, s26, 0x2200
	s_subb_u32 s27, s27, 0
	global_load_ushort v122, v74, s[26:27]
	s_sub_u32 s26, s26, 0x2200
	s_subb_u32 s27, s27, 0
	global_load_ushort v121, v74, s[26:27]
	s_sub_u32 s26, s26, 0x2200
	s_subb_u32 s27, s27, 0
	global_load_ushort v120, v74, s[26:27]
	s_sub_u32 s26, s26, 0x2200
	s_subb_u32 s27, s27, 0
	global_load_ushort v119, v74, s[26:27]
	s_sub_u32 s26, s26, 0x2200
	s_subb_u32 s27, s27, 0
	global_load_ushort v118, v74, s[26:27]
	s_sub_u32 s26, s26, 0x2200
	s_subb_u32 s27, s27, 0
	global_load_ushort v117, v74, s[26:27]
	s_sub_u32 s26, s26, 0x2200
	s_subb_u32 s27, s27, 0
	global_load_ushort v116, v74, s[26:27]
	s_sub_u32 s26, s26, 0x2200
	s_subb_u32 s27, s27, 0
	global_load_dwordx4 v[132:135], v32, s[28:29] offset:160
	global_load_dwordx4 v[136:139], v32, s[28:29] offset:176
	ds_read_b128 v[92:95], v32 offset:36224
	ds_read_b128 v[96:99], v32 offset:36240
	ds_read_b128 v[100:103], v32 offset:36256
	ds_read_b128 v[104:107], v32 offset:36272
	s_waitcnt lgkmcnt(4)
	v_fma_f32 v152, v76, v12, v48
	v_fmac_f32_e32 v152, v77, v15
	v_fmac_f32_e32 v152, v78, v17
	v_fmac_f32_e32 v152, v79, v19
	v_fmac_f32_e32 v152, v80, v20
	v_fmac_f32_e32 v152, v81, v23
	v_fmac_f32_e32 v152, v82, v25
	v_fmac_f32_e32 v152, v83, v27
	v_fmac_f32_e32 v152, v84, v13
	v_fmac_f32_e32 v152, v85, v14
	v_fmac_f32_e32 v152, v86, v16
	v_fmac_f32_e32 v152, v87, v18
	v_fmac_f32_e32 v152, v88, v21
	v_fmac_f32_e32 v152, v89, v22
	v_fmac_f32_e32 v152, v90, v24
	v_fmac_f32_e32 v152, v91, v26
	v_min_f32_e32 v153, 0, v152
	v_mul_f32_e64 v154, |v152|, s52
	v_exp_f32_e32 v154, v154
	v_mul_f32_e32 v155, 0x3fb8aa3b, v49
	v_add_f32_e32 v154, 1.0, v154
	v_log_f32_e32 v154, v154
	v_exp_f32_e32 v155, v155
	s_waitcnt vmcnt(11)
	v_lshlrev_b32_e32 v156, 16, v115
	v_fmac_f32_e32 v153, 0xbf317218, v154
	v_mul_f32_e32 v157, v155, v156
	v_mul_f32_e32 v147, v131, v157
	v_fmac_f32_e32 v49, 0x3d800000, v153
	ds_read_b128 v[76:79], v32 offset:36160
	ds_read_b128 v[80:83], v32 offset:36176
	ds_read_b128 v[84:87], v32 offset:36192
	ds_read_b128 v[88:91], v32 offset:36208
	s_waitcnt lgkmcnt(4)
	v_fma_f32 v152, v92, v12, v48
	v_fmac_f32_e32 v152, v93, v15
	v_fmac_f32_e32 v152, v94, v17
	v_fmac_f32_e32 v152, v95, v19
	v_fmac_f32_e32 v152, v96, v20
	v_fmac_f32_e32 v152, v97, v23
	v_fmac_f32_e32 v152, v98, v25
	v_fmac_f32_e32 v152, v99, v27
	v_fmac_f32_e32 v152, v100, v13
	v_fmac_f32_e32 v152, v101, v14
	v_fmac_f32_e32 v152, v102, v16
	v_fmac_f32_e32 v152, v103, v18
	v_fmac_f32_e32 v152, v104, v21
	v_fmac_f32_e32 v152, v105, v22
	v_fmac_f32_e32 v152, v106, v24
	v_fmac_f32_e32 v152, v107, v26
	v_min_f32_e32 v153, 0, v152
	v_mul_f32_e64 v154, |v152|, s52
	v_exp_f32_e32 v154, v154
	v_mul_f32_e32 v155, 0x3fb8aa3b, v49
	v_add_f32_e32 v154, 1.0, v154
	v_log_f32_e32 v154, v154
	v_exp_f32_e32 v155, v155
	v_lshlrev_b32_e32 v156, 16, v114
	v_fmac_f32_e32 v153, 0xbf317218, v154
	v_mul_f32_e32 v157, v155, v156
	v_mul_f32_e32 v146, v130, v157
	v_fmac_f32_e32 v49, 0x3d800000, v153
	ds_read_b128 v[92:95], v32 offset:36096
	ds_read_b128 v[96:99], v32 offset:36112
	ds_read_b128 v[100:103], v32 offset:36128
	ds_read_b128 v[104:107], v32 offset:36144
	s_waitcnt lgkmcnt(4)
	v_fma_f32 v152, v76, v12, v48
	v_fmac_f32_e32 v152, v77, v15
	v_fmac_f32_e32 v152, v78, v17
	v_fmac_f32_e32 v152, v79, v19
	v_fmac_f32_e32 v152, v80, v20
	v_fmac_f32_e32 v152, v81, v23
	v_fmac_f32_e32 v152, v82, v25
	v_fmac_f32_e32 v152, v83, v27
	v_fmac_f32_e32 v152, v84, v13
	v_fmac_f32_e32 v152, v85, v14
	v_fmac_f32_e32 v152, v86, v16
	v_fmac_f32_e32 v152, v87, v18
	v_fmac_f32_e32 v152, v88, v21
	v_fmac_f32_e32 v152, v89, v22
	v_fmac_f32_e32 v152, v90, v24
	v_fmac_f32_e32 v152, v91, v26
	v_min_f32_e32 v153, 0, v152
	v_mul_f32_e64 v154, |v152|, s52
	v_exp_f32_e32 v154, v154
	v_mul_f32_e32 v155, 0x3fb8aa3b, v49
	v_add_f32_e32 v154, 1.0, v154
	v_log_f32_e32 v154, v154
	v_exp_f32_e32 v155, v155
	v_lshlrev_b32_e32 v156, 16, v113
	v_fmac_f32_e32 v153, 0xbf317218, v154
	v_mul_f32_e32 v157, v155, v156
	v_mul_f32_e32 v145, v129, v157
	v_fmac_f32_e32 v49, 0x3d800000, v153
	ds_read_b128 v[76:79], v32 offset:36032
	ds_read_b128 v[80:83], v32 offset:36048
	ds_read_b128 v[84:87], v32 offset:36064
	ds_read_b128 v[88:91], v32 offset:36080
	s_waitcnt lgkmcnt(4)
	v_fma_f32 v152, v92, v12, v48
	v_fmac_f32_e32 v152, v93, v15
	v_fmac_f32_e32 v152, v94, v17
	v_fmac_f32_e32 v152, v95, v19
	v_fmac_f32_e32 v152, v96, v20
	v_fmac_f32_e32 v152, v97, v23
	v_fmac_f32_e32 v152, v98, v25
	v_fmac_f32_e32 v152, v99, v27
	v_fmac_f32_e32 v152, v100, v13
	v_fmac_f32_e32 v152, v101, v14
	v_fmac_f32_e32 v152, v102, v16
	v_fmac_f32_e32 v152, v103, v18
	v_fmac_f32_e32 v152, v104, v21
	v_fmac_f32_e32 v152, v105, v22
	v_fmac_f32_e32 v152, v106, v24
	v_fmac_f32_e32 v152, v107, v26
	v_min_f32_e32 v153, 0, v152
	v_mul_f32_e64 v154, |v152|, s52
	v_exp_f32_e32 v154, v154
	v_mul_f32_e32 v155, 0x3fb8aa3b, v49
	v_add_f32_e32 v154, 1.0, v154
	v_log_f32_e32 v154, v154
	v_exp_f32_e32 v155, v155
	v_lshlrev_b32_e32 v156, 16, v112
	v_fmac_f32_e32 v153, 0xbf317218, v154
	v_mul_f32_e32 v157, v155, v156
	v_mul_f32_e32 v144, v128, v157
	v_fmac_f32_e32 v49, 0x3d800000, v153
	ds_read_b128 v[92:95], v32 offset:35968
	ds_read_b128 v[96:99], v32 offset:35984
	ds_read_b128 v[100:103], v32 offset:36000
	ds_read_b128 v[104:107], v32 offset:36016
	s_waitcnt lgkmcnt(4)
	v_fma_f32 v152, v76, v12, v48
	v_fmac_f32_e32 v152, v77, v15
	v_fmac_f32_e32 v152, v78, v17
	v_fmac_f32_e32 v152, v79, v19
	v_fmac_f32_e32 v152, v80, v20
	v_fmac_f32_e32 v152, v81, v23
	v_fmac_f32_e32 v152, v82, v25
	v_fmac_f32_e32 v152, v83, v27
	v_fmac_f32_e32 v152, v84, v13
	v_fmac_f32_e32 v152, v85, v14
	v_fmac_f32_e32 v152, v86, v16
	v_fmac_f32_e32 v152, v87, v18
	v_fmac_f32_e32 v152, v88, v21
	v_fmac_f32_e32 v152, v89, v22
	v_fmac_f32_e32 v152, v90, v24
	v_fmac_f32_e32 v152, v91, v26
	v_min_f32_e32 v153, 0, v152
	v_mul_f32_e64 v154, |v152|, s52
	v_exp_f32_e32 v154, v154
	v_mul_f32_e32 v155, 0x3fb8aa3b, v49
	v_add_f32_e32 v154, 1.0, v154
	v_log_f32_e32 v154, v154
	v_exp_f32_e32 v155, v155
	v_lshlrev_b32_e32 v156, 16, v111
	v_fmac_f32_e32 v153, 0xbf317218, v154
	v_mul_f32_e32 v157, v155, v156
	v_mul_f32_e32 v143, v127, v157
	v_fmac_f32_e32 v49, 0x3d800000, v153
	ds_read_b128 v[76:79], v32 offset:35904
	ds_read_b128 v[80:83], v32 offset:35920
	ds_read_b128 v[84:87], v32 offset:35936
	ds_read_b128 v[88:91], v32 offset:35952
	s_waitcnt lgkmcnt(4)
	v_fma_f32 v152, v92, v12, v48
	v_fmac_f32_e32 v152, v93, v15
	v_fmac_f32_e32 v152, v94, v17
	v_fmac_f32_e32 v152, v95, v19
	v_fmac_f32_e32 v152, v96, v20
	v_fmac_f32_e32 v152, v97, v23
	v_fmac_f32_e32 v152, v98, v25
	v_fmac_f32_e32 v152, v99, v27
	v_fmac_f32_e32 v152, v100, v13
	v_fmac_f32_e32 v152, v101, v14
	v_fmac_f32_e32 v152, v102, v16
	v_fmac_f32_e32 v152, v103, v18
	v_fmac_f32_e32 v152, v104, v21
	v_fmac_f32_e32 v152, v105, v22
	v_fmac_f32_e32 v152, v106, v24
	v_fmac_f32_e32 v152, v107, v26
	v_min_f32_e32 v153, 0, v152
	v_mul_f32_e64 v154, |v152|, s52
	v_exp_f32_e32 v154, v154
	v_mul_f32_e32 v155, 0x3fb8aa3b, v49
	v_add_f32_e32 v154, 1.0, v154
	v_log_f32_e32 v154, v154
	v_exp_f32_e32 v155, v155
	v_lshlrev_b32_e32 v156, 16, v110
	v_fmac_f32_e32 v153, 0xbf317218, v154
	v_mul_f32_e32 v157, v155, v156
	v_mul_f32_e32 v142, v126, v157
	v_fmac_f32_e32 v49, 0x3d800000, v153
	ds_read_b128 v[92:95], v32 offset:35840
	ds_read_b128 v[96:99], v32 offset:35856
	ds_read_b128 v[100:103], v32 offset:35872
	ds_read_b128 v[104:107], v32 offset:35888
	s_waitcnt lgkmcnt(4)
	v_fma_f32 v152, v76, v12, v48
	v_fmac_f32_e32 v152, v77, v15
	v_fmac_f32_e32 v152, v78, v17
	v_fmac_f32_e32 v152, v79, v19
	v_fmac_f32_e32 v152, v80, v20
	v_fmac_f32_e32 v152, v81, v23
	v_fmac_f32_e32 v152, v82, v25
	v_fmac_f32_e32 v152, v83, v27
	v_fmac_f32_e32 v152, v84, v13
	v_fmac_f32_e32 v152, v85, v14
	v_fmac_f32_e32 v152, v86, v16
	v_fmac_f32_e32 v152, v87, v18
	v_fmac_f32_e32 v152, v88, v21
	v_fmac_f32_e32 v152, v89, v22
	v_fmac_f32_e32 v152, v90, v24
	v_fmac_f32_e32 v152, v91, v26
	v_min_f32_e32 v153, 0, v152
	v_mul_f32_e64 v154, |v152|, s52
	v_exp_f32_e32 v154, v154
	v_mul_f32_e32 v155, 0x3fb8aa3b, v49
	v_add_f32_e32 v154, 1.0, v154
	v_log_f32_e32 v154, v154
	v_exp_f32_e32 v155, v155
	v_lshlrev_b32_e32 v156, 16, v109
	v_fmac_f32_e32 v153, 0xbf317218, v154
	v_mul_f32_e32 v157, v155, v156
	v_mul_f32_e32 v141, v125, v157
	v_fmac_f32_e32 v49, 0x3d800000, v153
	ds_read_b128 v[76:79], v32 offset:35776
	ds_read_b128 v[80:83], v32 offset:35792
	ds_read_b128 v[84:87], v32 offset:35808
	ds_read_b128 v[88:91], v32 offset:35824
	s_waitcnt lgkmcnt(4)
	v_fma_f32 v152, v92, v12, v48
	v_fmac_f32_e32 v152, v93, v15
	v_fmac_f32_e32 v152, v94, v17
	v_fmac_f32_e32 v152, v95, v19
	v_fmac_f32_e32 v152, v96, v20
	v_fmac_f32_e32 v152, v97, v23
	v_fmac_f32_e32 v152, v98, v25
	v_fmac_f32_e32 v152, v99, v27
	v_fmac_f32_e32 v152, v100, v13
	v_fmac_f32_e32 v152, v101, v14
	v_fmac_f32_e32 v152, v102, v16
	v_fmac_f32_e32 v152, v103, v18
	v_fmac_f32_e32 v152, v104, v21
	v_fmac_f32_e32 v152, v105, v22
	v_fmac_f32_e32 v152, v106, v24
	v_fmac_f32_e32 v152, v107, v26
	v_min_f32_e32 v153, 0, v152
	v_mul_f32_e64 v154, |v152|, s52
	v_exp_f32_e32 v154, v154
	v_mul_f32_e32 v155, 0x3fb8aa3b, v49
	v_add_f32_e32 v154, 1.0, v154
	v_log_f32_e32 v154, v154
	v_exp_f32_e32 v155, v155
	v_lshlrev_b32_e32 v156, 16, v108
	v_fmac_f32_e32 v153, 0xbf317218, v154
	v_mul_f32_e32 v157, v155, v156
	v_mul_f32_e32 v140, v124, v157
	v_fmac_f32_e32 v49, 0x3d800000, v153
	v_cvt_pk_bf16_f32 v148, v140, v141
	v_cvt_pk_bf16_f32 v149, v142, v143
	v_cvt_pk_bf16_f32 v150, v144, v145
	v_cvt_pk_bf16_f32 v151, v146, v147
	global_store_dwordx4 v[28:29], v[148:151], off offset:96
	global_load_ushort v115, v74, s[26:27]
	s_sub_u32 s26, s26, 0x2200
	s_subb_u32 s27, s27, 0
	global_load_ushort v114, v74, s[26:27]
	s_sub_u32 s26, s26, 0x2200
	s_subb_u32 s27, s27, 0
	global_load_ushort v113, v74, s[26:27]
	s_sub_u32 s26, s26, 0x2200
	s_subb_u32 s27, s27, 0
	global_load_ushort v112, v74, s[26:27]
	s_sub_u32 s26, s26, 0x2200
	s_subb_u32 s27, s27, 0
	global_load_ushort v111, v74, s[26:27]
	s_sub_u32 s26, s26, 0x2200
	s_subb_u32 s27, s27, 0
	global_load_ushort v110, v74, s[26:27]
	s_sub_u32 s26, s26, 0x2200
	s_subb_u32 s27, s27, 0
	global_load_ushort v109, v74, s[26:27]
	s_sub_u32 s26, s26, 0x2200
	s_subb_u32 s27, s27, 0
	global_load_ushort v108, v74, s[26:27]
	s_sub_u32 s26, s26, 0x2200
	s_subb_u32 s27, s27, 0
	global_load_dwordx4 v[124:127], v32, s[28:29] offset:128
	global_load_dwordx4 v[128:131], v32, s[28:29] offset:144
	ds_read_b128 v[92:95], v32 offset:35712
	ds_read_b128 v[96:99], v32 offset:35728
	ds_read_b128 v[100:103], v32 offset:35744
	ds_read_b128 v[104:107], v32 offset:35760
	s_waitcnt lgkmcnt(4)
	v_fma_f32 v152, v76, v12, v48
	v_fmac_f32_e32 v152, v77, v15
	v_fmac_f32_e32 v152, v78, v17
	v_fmac_f32_e32 v152, v79, v19
	v_fmac_f32_e32 v152, v80, v20
	v_fmac_f32_e32 v152, v81, v23
	v_fmac_f32_e32 v152, v82, v25
	v_fmac_f32_e32 v152, v83, v27
	v_fmac_f32_e32 v152, v84, v13
	v_fmac_f32_e32 v152, v85, v14
	v_fmac_f32_e32 v152, v86, v16
	v_fmac_f32_e32 v152, v87, v18
	v_fmac_f32_e32 v152, v88, v21
	v_fmac_f32_e32 v152, v89, v22
	v_fmac_f32_e32 v152, v90, v24
	v_fmac_f32_e32 v152, v91, v26
	v_min_f32_e32 v153, 0, v152
	v_mul_f32_e64 v154, |v152|, s52
	v_exp_f32_e32 v154, v154
	v_mul_f32_e32 v155, 0x3fb8aa3b, v49
	v_add_f32_e32 v154, 1.0, v154
	v_log_f32_e32 v154, v154
	v_exp_f32_e32 v155, v155
	s_waitcnt vmcnt(11)
	v_lshlrev_b32_e32 v156, 16, v123
	v_fmac_f32_e32 v153, 0xbf317218, v154
	v_mul_f32_e32 v157, v155, v156
	v_mul_f32_e32 v147, v139, v157
	v_fmac_f32_e32 v49, 0x3d800000, v153
	ds_read_b128 v[76:79], v32 offset:35648
	ds_read_b128 v[80:83], v32 offset:35664
	ds_read_b128 v[84:87], v32 offset:35680
	ds_read_b128 v[88:91], v32 offset:35696
	s_waitcnt lgkmcnt(4)
	v_fma_f32 v152, v92, v12, v48
	v_fmac_f32_e32 v152, v93, v15
	v_fmac_f32_e32 v152, v94, v17
	v_fmac_f32_e32 v152, v95, v19
	v_fmac_f32_e32 v152, v96, v20
	v_fmac_f32_e32 v152, v97, v23
	v_fmac_f32_e32 v152, v98, v25
	v_fmac_f32_e32 v152, v99, v27
	v_fmac_f32_e32 v152, v100, v13
	v_fmac_f32_e32 v152, v101, v14
	v_fmac_f32_e32 v152, v102, v16
	v_fmac_f32_e32 v152, v103, v18
	v_fmac_f32_e32 v152, v104, v21
	v_fmac_f32_e32 v152, v105, v22
	v_fmac_f32_e32 v152, v106, v24
	v_fmac_f32_e32 v152, v107, v26
	v_min_f32_e32 v153, 0, v152
	v_mul_f32_e64 v154, |v152|, s52
	v_exp_f32_e32 v154, v154
	v_mul_f32_e32 v155, 0x3fb8aa3b, v49
	v_add_f32_e32 v154, 1.0, v154
	v_log_f32_e32 v154, v154
	v_exp_f32_e32 v155, v155
	v_lshlrev_b32_e32 v156, 16, v122
	v_fmac_f32_e32 v153, 0xbf317218, v154
	v_mul_f32_e32 v157, v155, v156
	v_mul_f32_e32 v146, v138, v157
	v_fmac_f32_e32 v49, 0x3d800000, v153
	ds_read_b128 v[92:95], v32 offset:35584
	ds_read_b128 v[96:99], v32 offset:35600
	ds_read_b128 v[100:103], v32 offset:35616
	ds_read_b128 v[104:107], v32 offset:35632
	s_waitcnt lgkmcnt(4)
	v_fma_f32 v152, v76, v12, v48
	v_fmac_f32_e32 v152, v77, v15
	v_fmac_f32_e32 v152, v78, v17
	v_fmac_f32_e32 v152, v79, v19
	v_fmac_f32_e32 v152, v80, v20
	v_fmac_f32_e32 v152, v81, v23
	v_fmac_f32_e32 v152, v82, v25
	v_fmac_f32_e32 v152, v83, v27
	v_fmac_f32_e32 v152, v84, v13
	v_fmac_f32_e32 v152, v85, v14
	v_fmac_f32_e32 v152, v86, v16
	v_fmac_f32_e32 v152, v87, v18
	v_fmac_f32_e32 v152, v88, v21
	v_fmac_f32_e32 v152, v89, v22
	v_fmac_f32_e32 v152, v90, v24
	v_fmac_f32_e32 v152, v91, v26
	v_min_f32_e32 v153, 0, v152
	v_mul_f32_e64 v154, |v152|, s52
	v_exp_f32_e32 v154, v154
	v_mul_f32_e32 v155, 0x3fb8aa3b, v49
	v_add_f32_e32 v154, 1.0, v154
	v_log_f32_e32 v154, v154
	v_exp_f32_e32 v155, v155
	v_lshlrev_b32_e32 v156, 16, v121
	v_fmac_f32_e32 v153, 0xbf317218, v154
	v_mul_f32_e32 v157, v155, v156
	v_mul_f32_e32 v145, v137, v157
	v_fmac_f32_e32 v49, 0x3d800000, v153
	ds_read_b128 v[76:79], v32 offset:35520
	ds_read_b128 v[80:83], v32 offset:35536
	ds_read_b128 v[84:87], v32 offset:35552
	ds_read_b128 v[88:91], v32 offset:35568
	s_waitcnt lgkmcnt(4)
	v_fma_f32 v152, v92, v12, v48
	v_fmac_f32_e32 v152, v93, v15
	v_fmac_f32_e32 v152, v94, v17
	v_fmac_f32_e32 v152, v95, v19
	v_fmac_f32_e32 v152, v96, v20
	v_fmac_f32_e32 v152, v97, v23
	v_fmac_f32_e32 v152, v98, v25
	v_fmac_f32_e32 v152, v99, v27
	v_fmac_f32_e32 v152, v100, v13
	v_fmac_f32_e32 v152, v101, v14
	v_fmac_f32_e32 v152, v102, v16
	v_fmac_f32_e32 v152, v103, v18
	v_fmac_f32_e32 v152, v104, v21
	v_fmac_f32_e32 v152, v105, v22
	v_fmac_f32_e32 v152, v106, v24
	v_fmac_f32_e32 v152, v107, v26
	v_min_f32_e32 v153, 0, v152
	v_mul_f32_e64 v154, |v152|, s52
	v_exp_f32_e32 v154, v154
	v_mul_f32_e32 v155, 0x3fb8aa3b, v49
	v_add_f32_e32 v154, 1.0, v154
	v_log_f32_e32 v154, v154
	v_exp_f32_e32 v155, v155
	v_lshlrev_b32_e32 v156, 16, v120
	v_fmac_f32_e32 v153, 0xbf317218, v154
	v_mul_f32_e32 v157, v155, v156
	v_mul_f32_e32 v144, v136, v157
	v_fmac_f32_e32 v49, 0x3d800000, v153
	ds_read_b128 v[92:95], v32 offset:35456
	ds_read_b128 v[96:99], v32 offset:35472
	ds_read_b128 v[100:103], v32 offset:35488
	ds_read_b128 v[104:107], v32 offset:35504
	s_waitcnt lgkmcnt(4)
	v_fma_f32 v152, v76, v12, v48
	v_fmac_f32_e32 v152, v77, v15
	v_fmac_f32_e32 v152, v78, v17
	v_fmac_f32_e32 v152, v79, v19
	v_fmac_f32_e32 v152, v80, v20
	v_fmac_f32_e32 v152, v81, v23
	v_fmac_f32_e32 v152, v82, v25
	v_fmac_f32_e32 v152, v83, v27
	v_fmac_f32_e32 v152, v84, v13
	v_fmac_f32_e32 v152, v85, v14
	v_fmac_f32_e32 v152, v86, v16
	v_fmac_f32_e32 v152, v87, v18
	v_fmac_f32_e32 v152, v88, v21
	v_fmac_f32_e32 v152, v89, v22
	v_fmac_f32_e32 v152, v90, v24
	v_fmac_f32_e32 v152, v91, v26
	v_min_f32_e32 v153, 0, v152
	v_mul_f32_e64 v154, |v152|, s52
	v_exp_f32_e32 v154, v154
	v_mul_f32_e32 v155, 0x3fb8aa3b, v49
	v_add_f32_e32 v154, 1.0, v154
	v_log_f32_e32 v154, v154
	v_exp_f32_e32 v155, v155
	v_lshlrev_b32_e32 v156, 16, v119
	v_fmac_f32_e32 v153, 0xbf317218, v154
	v_mul_f32_e32 v157, v155, v156
	v_mul_f32_e32 v143, v135, v157
	v_fmac_f32_e32 v49, 0x3d800000, v153
	ds_read_b128 v[76:79], v32 offset:35392
	ds_read_b128 v[80:83], v32 offset:35408
	ds_read_b128 v[84:87], v32 offset:35424
	ds_read_b128 v[88:91], v32 offset:35440
	s_waitcnt lgkmcnt(4)
	v_fma_f32 v152, v92, v12, v48
	v_fmac_f32_e32 v152, v93, v15
	v_fmac_f32_e32 v152, v94, v17
	v_fmac_f32_e32 v152, v95, v19
	v_fmac_f32_e32 v152, v96, v20
	v_fmac_f32_e32 v152, v97, v23
	v_fmac_f32_e32 v152, v98, v25
	v_fmac_f32_e32 v152, v99, v27
	v_fmac_f32_e32 v152, v100, v13
	v_fmac_f32_e32 v152, v101, v14
	v_fmac_f32_e32 v152, v102, v16
	v_fmac_f32_e32 v152, v103, v18
	v_fmac_f32_e32 v152, v104, v21
	v_fmac_f32_e32 v152, v105, v22
	v_fmac_f32_e32 v152, v106, v24
	v_fmac_f32_e32 v152, v107, v26
	v_min_f32_e32 v153, 0, v152
	v_mul_f32_e64 v154, |v152|, s52
	v_exp_f32_e32 v154, v154
	v_mul_f32_e32 v155, 0x3fb8aa3b, v49
	v_add_f32_e32 v154, 1.0, v154
	v_log_f32_e32 v154, v154
	v_exp_f32_e32 v155, v155
	v_lshlrev_b32_e32 v156, 16, v118
	v_fmac_f32_e32 v153, 0xbf317218, v154
	v_mul_f32_e32 v157, v155, v156
	v_mul_f32_e32 v142, v134, v157
	v_fmac_f32_e32 v49, 0x3d800000, v153
	ds_read_b128 v[92:95], v32 offset:35328
	ds_read_b128 v[96:99], v32 offset:35344
	ds_read_b128 v[100:103], v32 offset:35360
	ds_read_b128 v[104:107], v32 offset:35376
	s_waitcnt lgkmcnt(4)
	v_fma_f32 v152, v76, v12, v48
	v_fmac_f32_e32 v152, v77, v15
	v_fmac_f32_e32 v152, v78, v17
	v_fmac_f32_e32 v152, v79, v19
	v_fmac_f32_e32 v152, v80, v20
	v_fmac_f32_e32 v152, v81, v23
	v_fmac_f32_e32 v152, v82, v25
	v_fmac_f32_e32 v152, v83, v27
	v_fmac_f32_e32 v152, v84, v13
	v_fmac_f32_e32 v152, v85, v14
	v_fmac_f32_e32 v152, v86, v16
	v_fmac_f32_e32 v152, v87, v18
	v_fmac_f32_e32 v152, v88, v21
	v_fmac_f32_e32 v152, v89, v22
	v_fmac_f32_e32 v152, v90, v24
	v_fmac_f32_e32 v152, v91, v26
	v_min_f32_e32 v153, 0, v152
	v_mul_f32_e64 v154, |v152|, s52
	v_exp_f32_e32 v154, v154
	v_mul_f32_e32 v155, 0x3fb8aa3b, v49
	v_add_f32_e32 v154, 1.0, v154
	v_log_f32_e32 v154, v154
	v_exp_f32_e32 v155, v155
	v_lshlrev_b32_e32 v156, 16, v117
	v_fmac_f32_e32 v153, 0xbf317218, v154
	v_mul_f32_e32 v157, v155, v156
	v_mul_f32_e32 v141, v133, v157
	v_fmac_f32_e32 v49, 0x3d800000, v153
	ds_read_b128 v[76:79], v32 offset:35264
	ds_read_b128 v[80:83], v32 offset:35280
	ds_read_b128 v[84:87], v32 offset:35296
	ds_read_b128 v[88:91], v32 offset:35312
	s_waitcnt lgkmcnt(4)
	v_fma_f32 v152, v92, v12, v48
	v_fmac_f32_e32 v152, v93, v15
	v_fmac_f32_e32 v152, v94, v17
	v_fmac_f32_e32 v152, v95, v19
	v_fmac_f32_e32 v152, v96, v20
	v_fmac_f32_e32 v152, v97, v23
	v_fmac_f32_e32 v152, v98, v25
	v_fmac_f32_e32 v152, v99, v27
	v_fmac_f32_e32 v152, v100, v13
	v_fmac_f32_e32 v152, v101, v14
	v_fmac_f32_e32 v152, v102, v16
	v_fmac_f32_e32 v152, v103, v18
	v_fmac_f32_e32 v152, v104, v21
	v_fmac_f32_e32 v152, v105, v22
	v_fmac_f32_e32 v152, v106, v24
	v_fmac_f32_e32 v152, v107, v26
	v_min_f32_e32 v153, 0, v152
	v_mul_f32_e64 v154, |v152|, s52
	v_exp_f32_e32 v154, v154
	v_mul_f32_e32 v155, 0x3fb8aa3b, v49
	v_add_f32_e32 v154, 1.0, v154
	v_log_f32_e32 v154, v154
	v_exp_f32_e32 v155, v155
	v_lshlrev_b32_e32 v156, 16, v116
	v_fmac_f32_e32 v153, 0xbf317218, v154
	v_mul_f32_e32 v157, v155, v156
	v_mul_f32_e32 v140, v132, v157
	v_fmac_f32_e32 v49, 0x3d800000, v153
	v_cvt_pk_bf16_f32 v148, v140, v141
	v_cvt_pk_bf16_f32 v149, v142, v143
	v_cvt_pk_bf16_f32 v150, v144, v145
	v_cvt_pk_bf16_f32 v151, v146, v147
	global_store_dwordx4 v[28:29], v[148:151], off offset:80
	global_load_ushort v123, v74, s[26:27]
	s_sub_u32 s26, s26, 0x2200
	s_subb_u32 s27, s27, 0
	global_load_ushort v122, v74, s[26:27]
	s_sub_u32 s26, s26, 0x2200
	s_subb_u32 s27, s27, 0
	global_load_ushort v121, v74, s[26:27]
	s_sub_u32 s26, s26, 0x2200
	s_subb_u32 s27, s27, 0
	global_load_ushort v120, v74, s[26:27]
	s_sub_u32 s26, s26, 0x2200
	s_subb_u32 s27, s27, 0
	global_load_ushort v119, v74, s[26:27]
	s_sub_u32 s26, s26, 0x2200
	s_subb_u32 s27, s27, 0
	global_load_ushort v118, v74, s[26:27]
	s_sub_u32 s26, s26, 0x2200
	s_subb_u32 s27, s27, 0
	global_load_ushort v117, v74, s[26:27]
	s_sub_u32 s26, s26, 0x2200
	s_subb_u32 s27, s27, 0
	global_load_ushort v116, v74, s[26:27]
	s_sub_u32 s26, s26, 0x2200
	s_subb_u32 s27, s27, 0
	global_load_dwordx4 v[132:135], v32, s[28:29] offset:96
	global_load_dwordx4 v[136:139], v32, s[28:29] offset:112
	ds_read_b128 v[92:95], v32 offset:35200
	ds_read_b128 v[96:99], v32 offset:35216
	ds_read_b128 v[100:103], v32 offset:35232
	ds_read_b128 v[104:107], v32 offset:35248
	s_waitcnt lgkmcnt(4)
	v_fma_f32 v152, v76, v12, v48
	v_fmac_f32_e32 v152, v77, v15
	v_fmac_f32_e32 v152, v78, v17
	v_fmac_f32_e32 v152, v79, v19
	v_fmac_f32_e32 v152, v80, v20
	v_fmac_f32_e32 v152, v81, v23
	v_fmac_f32_e32 v152, v82, v25
	v_fmac_f32_e32 v152, v83, v27
	v_fmac_f32_e32 v152, v84, v13
	v_fmac_f32_e32 v152, v85, v14
	v_fmac_f32_e32 v152, v86, v16
	v_fmac_f32_e32 v152, v87, v18
	v_fmac_f32_e32 v152, v88, v21
	v_fmac_f32_e32 v152, v89, v22
	v_fmac_f32_e32 v152, v90, v24
	v_fmac_f32_e32 v152, v91, v26
	v_min_f32_e32 v153, 0, v152
	v_mul_f32_e64 v154, |v152|, s52
	v_exp_f32_e32 v154, v154
	v_mul_f32_e32 v155, 0x3fb8aa3b, v49
	v_add_f32_e32 v154, 1.0, v154
	v_log_f32_e32 v154, v154
	v_exp_f32_e32 v155, v155
	s_waitcnt vmcnt(11)
	v_lshlrev_b32_e32 v156, 16, v115
	v_fmac_f32_e32 v153, 0xbf317218, v154
	v_mul_f32_e32 v157, v155, v156
	v_mul_f32_e32 v147, v131, v157
	v_fmac_f32_e32 v49, 0x3d800000, v153
	ds_read_b128 v[76:79], v32 offset:35136
	ds_read_b128 v[80:83], v32 offset:35152
	ds_read_b128 v[84:87], v32 offset:35168
	ds_read_b128 v[88:91], v32 offset:35184
	s_waitcnt lgkmcnt(4)
	v_fma_f32 v152, v92, v12, v48
	v_fmac_f32_e32 v152, v93, v15
	v_fmac_f32_e32 v152, v94, v17
	v_fmac_f32_e32 v152, v95, v19
	v_fmac_f32_e32 v152, v96, v20
	v_fmac_f32_e32 v152, v97, v23
	v_fmac_f32_e32 v152, v98, v25
	v_fmac_f32_e32 v152, v99, v27
	v_fmac_f32_e32 v152, v100, v13
	v_fmac_f32_e32 v152, v101, v14
	v_fmac_f32_e32 v152, v102, v16
	v_fmac_f32_e32 v152, v103, v18
	v_fmac_f32_e32 v152, v104, v21
	v_fmac_f32_e32 v152, v105, v22
	v_fmac_f32_e32 v152, v106, v24
	v_fmac_f32_e32 v152, v107, v26
	v_min_f32_e32 v153, 0, v152
	v_mul_f32_e64 v154, |v152|, s52
	v_exp_f32_e32 v154, v154
	v_mul_f32_e32 v155, 0x3fb8aa3b, v49
	v_add_f32_e32 v154, 1.0, v154
	v_log_f32_e32 v154, v154
	v_exp_f32_e32 v155, v155
	v_lshlrev_b32_e32 v156, 16, v114
	v_fmac_f32_e32 v153, 0xbf317218, v154
	v_mul_f32_e32 v157, v155, v156
	v_mul_f32_e32 v146, v130, v157
	v_fmac_f32_e32 v49, 0x3d800000, v153
	ds_read_b128 v[92:95], v32 offset:35072
	ds_read_b128 v[96:99], v32 offset:35088
	ds_read_b128 v[100:103], v32 offset:35104
	ds_read_b128 v[104:107], v32 offset:35120
	s_waitcnt lgkmcnt(4)
	v_fma_f32 v152, v76, v12, v48
	v_fmac_f32_e32 v152, v77, v15
	v_fmac_f32_e32 v152, v78, v17
	v_fmac_f32_e32 v152, v79, v19
	v_fmac_f32_e32 v152, v80, v20
	v_fmac_f32_e32 v152, v81, v23
	v_fmac_f32_e32 v152, v82, v25
	v_fmac_f32_e32 v152, v83, v27
	v_fmac_f32_e32 v152, v84, v13
	v_fmac_f32_e32 v152, v85, v14
	v_fmac_f32_e32 v152, v86, v16
	v_fmac_f32_e32 v152, v87, v18
	v_fmac_f32_e32 v152, v88, v21
	v_fmac_f32_e32 v152, v89, v22
	v_fmac_f32_e32 v152, v90, v24
	v_fmac_f32_e32 v152, v91, v26
	v_min_f32_e32 v153, 0, v152
	v_mul_f32_e64 v154, |v152|, s52
	v_exp_f32_e32 v154, v154
	v_mul_f32_e32 v155, 0x3fb8aa3b, v49
	v_add_f32_e32 v154, 1.0, v154
	v_log_f32_e32 v154, v154
	v_exp_f32_e32 v155, v155
	v_lshlrev_b32_e32 v156, 16, v113
	v_fmac_f32_e32 v153, 0xbf317218, v154
	v_mul_f32_e32 v157, v155, v156
	v_mul_f32_e32 v145, v129, v157
	v_fmac_f32_e32 v49, 0x3d800000, v153
	ds_read_b128 v[76:79], v32 offset:35008
	ds_read_b128 v[80:83], v32 offset:35024
	ds_read_b128 v[84:87], v32 offset:35040
	ds_read_b128 v[88:91], v32 offset:35056
	s_waitcnt lgkmcnt(4)
	v_fma_f32 v152, v92, v12, v48
	v_fmac_f32_e32 v152, v93, v15
	v_fmac_f32_e32 v152, v94, v17
	v_fmac_f32_e32 v152, v95, v19
	v_fmac_f32_e32 v152, v96, v20
	v_fmac_f32_e32 v152, v97, v23
	v_fmac_f32_e32 v152, v98, v25
	v_fmac_f32_e32 v152, v99, v27
	v_fmac_f32_e32 v152, v100, v13
	v_fmac_f32_e32 v152, v101, v14
	v_fmac_f32_e32 v152, v102, v16
	v_fmac_f32_e32 v152, v103, v18
	v_fmac_f32_e32 v152, v104, v21
	v_fmac_f32_e32 v152, v105, v22
	v_fmac_f32_e32 v152, v106, v24
	v_fmac_f32_e32 v152, v107, v26
	v_min_f32_e32 v153, 0, v152
	v_mul_f32_e64 v154, |v152|, s52
	v_exp_f32_e32 v154, v154
	v_mul_f32_e32 v155, 0x3fb8aa3b, v49
	v_add_f32_e32 v154, 1.0, v154
	v_log_f32_e32 v154, v154
	v_exp_f32_e32 v155, v155
	v_lshlrev_b32_e32 v156, 16, v112
	v_fmac_f32_e32 v153, 0xbf317218, v154
	v_mul_f32_e32 v157, v155, v156
	v_mul_f32_e32 v144, v128, v157
	v_fmac_f32_e32 v49, 0x3d800000, v153
	ds_read_b128 v[92:95], v32 offset:34944
	ds_read_b128 v[96:99], v32 offset:34960
	ds_read_b128 v[100:103], v32 offset:34976
	ds_read_b128 v[104:107], v32 offset:34992
	s_waitcnt lgkmcnt(4)
	v_fma_f32 v152, v76, v12, v48
	v_fmac_f32_e32 v152, v77, v15
	v_fmac_f32_e32 v152, v78, v17
	v_fmac_f32_e32 v152, v79, v19
	v_fmac_f32_e32 v152, v80, v20
	v_fmac_f32_e32 v152, v81, v23
	v_fmac_f32_e32 v152, v82, v25
	v_fmac_f32_e32 v152, v83, v27
	v_fmac_f32_e32 v152, v84, v13
	v_fmac_f32_e32 v152, v85, v14
	v_fmac_f32_e32 v152, v86, v16
	v_fmac_f32_e32 v152, v87, v18
	v_fmac_f32_e32 v152, v88, v21
	v_fmac_f32_e32 v152, v89, v22
	v_fmac_f32_e32 v152, v90, v24
	v_fmac_f32_e32 v152, v91, v26
	v_min_f32_e32 v153, 0, v152
	v_mul_f32_e64 v154, |v152|, s52
	v_exp_f32_e32 v154, v154
	v_mul_f32_e32 v155, 0x3fb8aa3b, v49
	v_add_f32_e32 v154, 1.0, v154
	v_log_f32_e32 v154, v154
	v_exp_f32_e32 v155, v155
	v_lshlrev_b32_e32 v156, 16, v111
	v_fmac_f32_e32 v153, 0xbf317218, v154
	v_mul_f32_e32 v157, v155, v156
	v_mul_f32_e32 v143, v127, v157
	v_fmac_f32_e32 v49, 0x3d800000, v153
	ds_read_b128 v[76:79], v32 offset:34880
	ds_read_b128 v[80:83], v32 offset:34896
	ds_read_b128 v[84:87], v32 offset:34912
	ds_read_b128 v[88:91], v32 offset:34928
	s_waitcnt lgkmcnt(4)
	v_fma_f32 v152, v92, v12, v48
	v_fmac_f32_e32 v152, v93, v15
	v_fmac_f32_e32 v152, v94, v17
	v_fmac_f32_e32 v152, v95, v19
	v_fmac_f32_e32 v152, v96, v20
	v_fmac_f32_e32 v152, v97, v23
	v_fmac_f32_e32 v152, v98, v25
	v_fmac_f32_e32 v152, v99, v27
	v_fmac_f32_e32 v152, v100, v13
	v_fmac_f32_e32 v152, v101, v14
	v_fmac_f32_e32 v152, v102, v16
	v_fmac_f32_e32 v152, v103, v18
	v_fmac_f32_e32 v152, v104, v21
	v_fmac_f32_e32 v152, v105, v22
	v_fmac_f32_e32 v152, v106, v24
	v_fmac_f32_e32 v152, v107, v26
	v_min_f32_e32 v153, 0, v152
	v_mul_f32_e64 v154, |v152|, s52
	v_exp_f32_e32 v154, v154
	v_mul_f32_e32 v155, 0x3fb8aa3b, v49
	v_add_f32_e32 v154, 1.0, v154
	v_log_f32_e32 v154, v154
	v_exp_f32_e32 v155, v155
	v_lshlrev_b32_e32 v156, 16, v110
	v_fmac_f32_e32 v153, 0xbf317218, v154
	v_mul_f32_e32 v157, v155, v156
	v_mul_f32_e32 v142, v126, v157
	v_fmac_f32_e32 v49, 0x3d800000, v153
	ds_read_b128 v[92:95], v32 offset:34816
	ds_read_b128 v[96:99], v32 offset:34832
	ds_read_b128 v[100:103], v32 offset:34848
	ds_read_b128 v[104:107], v32 offset:34864
	s_waitcnt lgkmcnt(4)
	v_fma_f32 v152, v76, v12, v48
	v_fmac_f32_e32 v152, v77, v15
	v_fmac_f32_e32 v152, v78, v17
	v_fmac_f32_e32 v152, v79, v19
	v_fmac_f32_e32 v152, v80, v20
	v_fmac_f32_e32 v152, v81, v23
	v_fmac_f32_e32 v152, v82, v25
	v_fmac_f32_e32 v152, v83, v27
	v_fmac_f32_e32 v152, v84, v13
	v_fmac_f32_e32 v152, v85, v14
	v_fmac_f32_e32 v152, v86, v16
	v_fmac_f32_e32 v152, v87, v18
	v_fmac_f32_e32 v152, v88, v21
	v_fmac_f32_e32 v152, v89, v22
	v_fmac_f32_e32 v152, v90, v24
	v_fmac_f32_e32 v152, v91, v26
	v_min_f32_e32 v153, 0, v152
	v_mul_f32_e64 v154, |v152|, s52
	v_exp_f32_e32 v154, v154
	v_mul_f32_e32 v155, 0x3fb8aa3b, v49
	v_add_f32_e32 v154, 1.0, v154
	v_log_f32_e32 v154, v154
	v_exp_f32_e32 v155, v155
	v_lshlrev_b32_e32 v156, 16, v109
	v_fmac_f32_e32 v153, 0xbf317218, v154
	v_mul_f32_e32 v157, v155, v156
	v_mul_f32_e32 v141, v125, v157
	v_fmac_f32_e32 v49, 0x3d800000, v153
	ds_read_b128 v[76:79], v32 offset:34752
	ds_read_b128 v[80:83], v32 offset:34768
	ds_read_b128 v[84:87], v32 offset:34784
	ds_read_b128 v[88:91], v32 offset:34800
	s_waitcnt lgkmcnt(4)
	v_fma_f32 v152, v92, v12, v48
	v_fmac_f32_e32 v152, v93, v15
	v_fmac_f32_e32 v152, v94, v17
	v_fmac_f32_e32 v152, v95, v19
	v_fmac_f32_e32 v152, v96, v20
	v_fmac_f32_e32 v152, v97, v23
	v_fmac_f32_e32 v152, v98, v25
	v_fmac_f32_e32 v152, v99, v27
	v_fmac_f32_e32 v152, v100, v13
	v_fmac_f32_e32 v152, v101, v14
	v_fmac_f32_e32 v152, v102, v16
	v_fmac_f32_e32 v152, v103, v18
	v_fmac_f32_e32 v152, v104, v21
	v_fmac_f32_e32 v152, v105, v22
	v_fmac_f32_e32 v152, v106, v24
	v_fmac_f32_e32 v152, v107, v26
	v_min_f32_e32 v153, 0, v152
	v_mul_f32_e64 v154, |v152|, s52
	v_exp_f32_e32 v154, v154
	v_mul_f32_e32 v155, 0x3fb8aa3b, v49
	v_add_f32_e32 v154, 1.0, v154
	v_log_f32_e32 v154, v154
	v_exp_f32_e32 v155, v155
	v_lshlrev_b32_e32 v156, 16, v108
	v_fmac_f32_e32 v153, 0xbf317218, v154
	v_mul_f32_e32 v157, v155, v156
	v_mul_f32_e32 v140, v124, v157
	v_fmac_f32_e32 v49, 0x3d800000, v153
	v_cvt_pk_bf16_f32 v148, v140, v141
	v_cvt_pk_bf16_f32 v149, v142, v143
	v_cvt_pk_bf16_f32 v150, v144, v145
	v_cvt_pk_bf16_f32 v151, v146, v147
	global_store_dwordx4 v[28:29], v[148:151], off offset:64
	global_load_ushort v115, v74, s[26:27]
	s_sub_u32 s26, s26, 0x2200
	s_subb_u32 s27, s27, 0
	global_load_ushort v114, v74, s[26:27]
	s_sub_u32 s26, s26, 0x2200
	s_subb_u32 s27, s27, 0
	global_load_ushort v113, v74, s[26:27]
	s_sub_u32 s26, s26, 0x2200
	s_subb_u32 s27, s27, 0
	global_load_ushort v112, v74, s[26:27]
	s_sub_u32 s26, s26, 0x2200
	s_subb_u32 s27, s27, 0
	global_load_ushort v111, v74, s[26:27]
	s_sub_u32 s26, s26, 0x2200
	s_subb_u32 s27, s27, 0
	global_load_ushort v110, v74, s[26:27]
	s_sub_u32 s26, s26, 0x2200
	s_subb_u32 s27, s27, 0
	global_load_ushort v109, v74, s[26:27]
	s_sub_u32 s26, s26, 0x2200
	s_subb_u32 s27, s27, 0
	global_load_ushort v108, v74, s[26:27]
	s_sub_u32 s26, s26, 0x2200
	s_subb_u32 s27, s27, 0
	global_load_dwordx4 v[124:127], v32, s[28:29] offset:64
	global_load_dwordx4 v[128:131], v32, s[28:29] offset:80
	ds_read_b128 v[92:95], v32 offset:34688
	ds_read_b128 v[96:99], v32 offset:34704
	ds_read_b128 v[100:103], v32 offset:34720
	ds_read_b128 v[104:107], v32 offset:34736
	s_waitcnt lgkmcnt(4)
	v_fma_f32 v152, v76, v12, v48
	v_fmac_f32_e32 v152, v77, v15
	v_fmac_f32_e32 v152, v78, v17
	v_fmac_f32_e32 v152, v79, v19
	v_fmac_f32_e32 v152, v80, v20
	v_fmac_f32_e32 v152, v81, v23
	v_fmac_f32_e32 v152, v82, v25
	v_fmac_f32_e32 v152, v83, v27
	v_fmac_f32_e32 v152, v84, v13
	v_fmac_f32_e32 v152, v85, v14
	v_fmac_f32_e32 v152, v86, v16
	v_fmac_f32_e32 v152, v87, v18
	v_fmac_f32_e32 v152, v88, v21
	v_fmac_f32_e32 v152, v89, v22
	v_fmac_f32_e32 v152, v90, v24
	v_fmac_f32_e32 v152, v91, v26
	v_min_f32_e32 v153, 0, v152
	v_mul_f32_e64 v154, |v152|, s52
	v_exp_f32_e32 v154, v154
	v_mul_f32_e32 v155, 0x3fb8aa3b, v49
	v_add_f32_e32 v154, 1.0, v154
	v_log_f32_e32 v154, v154
	v_exp_f32_e32 v155, v155
	s_waitcnt vmcnt(11)
	v_lshlrev_b32_e32 v156, 16, v123
	v_fmac_f32_e32 v153, 0xbf317218, v154
	v_mul_f32_e32 v157, v155, v156
	v_mul_f32_e32 v147, v139, v157
	v_fmac_f32_e32 v49, 0x3d800000, v153
	ds_read_b128 v[76:79], v32 offset:34624
	ds_read_b128 v[80:83], v32 offset:34640
	ds_read_b128 v[84:87], v32 offset:34656
	ds_read_b128 v[88:91], v32 offset:34672
	s_waitcnt lgkmcnt(4)
	v_fma_f32 v152, v92, v12, v48
	v_fmac_f32_e32 v152, v93, v15
	v_fmac_f32_e32 v152, v94, v17
	v_fmac_f32_e32 v152, v95, v19
	v_fmac_f32_e32 v152, v96, v20
	v_fmac_f32_e32 v152, v97, v23
	v_fmac_f32_e32 v152, v98, v25
	v_fmac_f32_e32 v152, v99, v27
	v_fmac_f32_e32 v152, v100, v13
	v_fmac_f32_e32 v152, v101, v14
	v_fmac_f32_e32 v152, v102, v16
	v_fmac_f32_e32 v152, v103, v18
	v_fmac_f32_e32 v152, v104, v21
	v_fmac_f32_e32 v152, v105, v22
	v_fmac_f32_e32 v152, v106, v24
	v_fmac_f32_e32 v152, v107, v26
	v_min_f32_e32 v153, 0, v152
	v_mul_f32_e64 v154, |v152|, s52
	v_exp_f32_e32 v154, v154
	v_mul_f32_e32 v155, 0x3fb8aa3b, v49
	v_add_f32_e32 v154, 1.0, v154
	v_log_f32_e32 v154, v154
	v_exp_f32_e32 v155, v155
	v_lshlrev_b32_e32 v156, 16, v122
	v_fmac_f32_e32 v153, 0xbf317218, v154
	v_mul_f32_e32 v157, v155, v156
	v_mul_f32_e32 v146, v138, v157
	v_fmac_f32_e32 v49, 0x3d800000, v153
	ds_read_b128 v[92:95], v32 offset:34560
	ds_read_b128 v[96:99], v32 offset:34576
	ds_read_b128 v[100:103], v32 offset:34592
	ds_read_b128 v[104:107], v32 offset:34608
	s_waitcnt lgkmcnt(4)
	v_fma_f32 v152, v76, v12, v48
	v_fmac_f32_e32 v152, v77, v15
	v_fmac_f32_e32 v152, v78, v17
	v_fmac_f32_e32 v152, v79, v19
	v_fmac_f32_e32 v152, v80, v20
	v_fmac_f32_e32 v152, v81, v23
	v_fmac_f32_e32 v152, v82, v25
	v_fmac_f32_e32 v152, v83, v27
	v_fmac_f32_e32 v152, v84, v13
	v_fmac_f32_e32 v152, v85, v14
	v_fmac_f32_e32 v152, v86, v16
	v_fmac_f32_e32 v152, v87, v18
	v_fmac_f32_e32 v152, v88, v21
	v_fmac_f32_e32 v152, v89, v22
	v_fmac_f32_e32 v152, v90, v24
	v_fmac_f32_e32 v152, v91, v26
	v_min_f32_e32 v153, 0, v152
	v_mul_f32_e64 v154, |v152|, s52
	v_exp_f32_e32 v154, v154
	v_mul_f32_e32 v155, 0x3fb8aa3b, v49
	v_add_f32_e32 v154, 1.0, v154
	v_log_f32_e32 v154, v154
	v_exp_f32_e32 v155, v155
	v_lshlrev_b32_e32 v156, 16, v121
	v_fmac_f32_e32 v153, 0xbf317218, v154
	v_mul_f32_e32 v157, v155, v156
	v_mul_f32_e32 v145, v137, v157
	v_fmac_f32_e32 v49, 0x3d800000, v153
	ds_read_b128 v[76:79], v32 offset:34496
	ds_read_b128 v[80:83], v32 offset:34512
	ds_read_b128 v[84:87], v32 offset:34528
	ds_read_b128 v[88:91], v32 offset:34544
	s_waitcnt lgkmcnt(4)
	v_fma_f32 v152, v92, v12, v48
	v_fmac_f32_e32 v152, v93, v15
	v_fmac_f32_e32 v152, v94, v17
	v_fmac_f32_e32 v152, v95, v19
	v_fmac_f32_e32 v152, v96, v20
	v_fmac_f32_e32 v152, v97, v23
	v_fmac_f32_e32 v152, v98, v25
	v_fmac_f32_e32 v152, v99, v27
	v_fmac_f32_e32 v152, v100, v13
	v_fmac_f32_e32 v152, v101, v14
	v_fmac_f32_e32 v152, v102, v16
	v_fmac_f32_e32 v152, v103, v18
	v_fmac_f32_e32 v152, v104, v21
	v_fmac_f32_e32 v152, v105, v22
	v_fmac_f32_e32 v152, v106, v24
	v_fmac_f32_e32 v152, v107, v26
	v_min_f32_e32 v153, 0, v152
	v_mul_f32_e64 v154, |v152|, s52
	v_exp_f32_e32 v154, v154
	v_mul_f32_e32 v155, 0x3fb8aa3b, v49
	v_add_f32_e32 v154, 1.0, v154
	v_log_f32_e32 v154, v154
	v_exp_f32_e32 v155, v155
	v_lshlrev_b32_e32 v156, 16, v120
	v_fmac_f32_e32 v153, 0xbf317218, v154
	v_mul_f32_e32 v157, v155, v156
	v_mul_f32_e32 v144, v136, v157
	v_fmac_f32_e32 v49, 0x3d800000, v153
	ds_read_b128 v[92:95], v32 offset:34432
	ds_read_b128 v[96:99], v32 offset:34448
	ds_read_b128 v[100:103], v32 offset:34464
	ds_read_b128 v[104:107], v32 offset:34480
	s_waitcnt lgkmcnt(4)
	v_fma_f32 v152, v76, v12, v48
	v_fmac_f32_e32 v152, v77, v15
	v_fmac_f32_e32 v152, v78, v17
	v_fmac_f32_e32 v152, v79, v19
	v_fmac_f32_e32 v152, v80, v20
	v_fmac_f32_e32 v152, v81, v23
	v_fmac_f32_e32 v152, v82, v25
	v_fmac_f32_e32 v152, v83, v27
	v_fmac_f32_e32 v152, v84, v13
	v_fmac_f32_e32 v152, v85, v14
	v_fmac_f32_e32 v152, v86, v16
	v_fmac_f32_e32 v152, v87, v18
	v_fmac_f32_e32 v152, v88, v21
	v_fmac_f32_e32 v152, v89, v22
	v_fmac_f32_e32 v152, v90, v24
	v_fmac_f32_e32 v152, v91, v26
	v_min_f32_e32 v153, 0, v152
	v_mul_f32_e64 v154, |v152|, s52
	v_exp_f32_e32 v154, v154
	v_mul_f32_e32 v155, 0x3fb8aa3b, v49
	v_add_f32_e32 v154, 1.0, v154
	v_log_f32_e32 v154, v154
	v_exp_f32_e32 v155, v155
	v_lshlrev_b32_e32 v156, 16, v119
	v_fmac_f32_e32 v153, 0xbf317218, v154
	v_mul_f32_e32 v157, v155, v156
	v_mul_f32_e32 v143, v135, v157
	v_fmac_f32_e32 v49, 0x3d800000, v153
	ds_read_b128 v[76:79], v32 offset:34368
	ds_read_b128 v[80:83], v32 offset:34384
	ds_read_b128 v[84:87], v32 offset:34400
	ds_read_b128 v[88:91], v32 offset:34416
	s_waitcnt lgkmcnt(4)
	v_fma_f32 v152, v92, v12, v48
	v_fmac_f32_e32 v152, v93, v15
	v_fmac_f32_e32 v152, v94, v17
	v_fmac_f32_e32 v152, v95, v19
	v_fmac_f32_e32 v152, v96, v20
	v_fmac_f32_e32 v152, v97, v23
	v_fmac_f32_e32 v152, v98, v25
	v_fmac_f32_e32 v152, v99, v27
	v_fmac_f32_e32 v152, v100, v13
	v_fmac_f32_e32 v152, v101, v14
	v_fmac_f32_e32 v152, v102, v16
	v_fmac_f32_e32 v152, v103, v18
	v_fmac_f32_e32 v152, v104, v21
	v_fmac_f32_e32 v152, v105, v22
	v_fmac_f32_e32 v152, v106, v24
	v_fmac_f32_e32 v152, v107, v26
	v_min_f32_e32 v153, 0, v152
	v_mul_f32_e64 v154, |v152|, s52
	v_exp_f32_e32 v154, v154
	v_mul_f32_e32 v155, 0x3fb8aa3b, v49
	v_add_f32_e32 v154, 1.0, v154
	v_log_f32_e32 v154, v154
	v_exp_f32_e32 v155, v155
	v_lshlrev_b32_e32 v156, 16, v118
	v_fmac_f32_e32 v153, 0xbf317218, v154
	v_mul_f32_e32 v157, v155, v156
	v_mul_f32_e32 v142, v134, v157
	v_fmac_f32_e32 v49, 0x3d800000, v153
	ds_read_b128 v[92:95], v32 offset:34304
	ds_read_b128 v[96:99], v32 offset:34320
	ds_read_b128 v[100:103], v32 offset:34336
	ds_read_b128 v[104:107], v32 offset:34352
	s_waitcnt lgkmcnt(4)
	v_fma_f32 v152, v76, v12, v48
	v_fmac_f32_e32 v152, v77, v15
	v_fmac_f32_e32 v152, v78, v17
	v_fmac_f32_e32 v152, v79, v19
	v_fmac_f32_e32 v152, v80, v20
	v_fmac_f32_e32 v152, v81, v23
	v_fmac_f32_e32 v152, v82, v25
	v_fmac_f32_e32 v152, v83, v27
	v_fmac_f32_e32 v152, v84, v13
	v_fmac_f32_e32 v152, v85, v14
	v_fmac_f32_e32 v152, v86, v16
	v_fmac_f32_e32 v152, v87, v18
	v_fmac_f32_e32 v152, v88, v21
	v_fmac_f32_e32 v152, v89, v22
	v_fmac_f32_e32 v152, v90, v24
	v_fmac_f32_e32 v152, v91, v26
	v_min_f32_e32 v153, 0, v152
	v_mul_f32_e64 v154, |v152|, s52
	v_exp_f32_e32 v154, v154
	v_mul_f32_e32 v155, 0x3fb8aa3b, v49
	v_add_f32_e32 v154, 1.0, v154
	v_log_f32_e32 v154, v154
	v_exp_f32_e32 v155, v155
	v_lshlrev_b32_e32 v156, 16, v117
	v_fmac_f32_e32 v153, 0xbf317218, v154
	v_mul_f32_e32 v157, v155, v156
	v_mul_f32_e32 v141, v133, v157
	v_fmac_f32_e32 v49, 0x3d800000, v153
	ds_read_b128 v[76:79], v32 offset:34240
	ds_read_b128 v[80:83], v32 offset:34256
	ds_read_b128 v[84:87], v32 offset:34272
	ds_read_b128 v[88:91], v32 offset:34288
	s_waitcnt lgkmcnt(4)
	v_fma_f32 v152, v92, v12, v48
	v_fmac_f32_e32 v152, v93, v15
	v_fmac_f32_e32 v152, v94, v17
	v_fmac_f32_e32 v152, v95, v19
	v_fmac_f32_e32 v152, v96, v20
	v_fmac_f32_e32 v152, v97, v23
	v_fmac_f32_e32 v152, v98, v25
	v_fmac_f32_e32 v152, v99, v27
	v_fmac_f32_e32 v152, v100, v13
	v_fmac_f32_e32 v152, v101, v14
	v_fmac_f32_e32 v152, v102, v16
	v_fmac_f32_e32 v152, v103, v18
	v_fmac_f32_e32 v152, v104, v21
	v_fmac_f32_e32 v152, v105, v22
	v_fmac_f32_e32 v152, v106, v24
	v_fmac_f32_e32 v152, v107, v26
	v_min_f32_e32 v153, 0, v152
	v_mul_f32_e64 v154, |v152|, s52
	v_exp_f32_e32 v154, v154
	v_mul_f32_e32 v155, 0x3fb8aa3b, v49
	v_add_f32_e32 v154, 1.0, v154
	v_log_f32_e32 v154, v154
	v_exp_f32_e32 v155, v155
	v_lshlrev_b32_e32 v156, 16, v116
	v_fmac_f32_e32 v153, 0xbf317218, v154
	v_mul_f32_e32 v157, v155, v156
	v_mul_f32_e32 v140, v132, v157
	v_fmac_f32_e32 v49, 0x3d800000, v153
	v_cvt_pk_bf16_f32 v148, v140, v141
	v_cvt_pk_bf16_f32 v149, v142, v143
	v_cvt_pk_bf16_f32 v150, v144, v145
	v_cvt_pk_bf16_f32 v151, v146, v147
	global_store_dwordx4 v[28:29], v[148:151], off offset:48
	global_load_ushort v123, v74, s[26:27]
	s_sub_u32 s26, s26, 0x2200
	s_subb_u32 s27, s27, 0
	global_load_ushort v122, v74, s[26:27]
	s_sub_u32 s26, s26, 0x2200
	s_subb_u32 s27, s27, 0
	global_load_ushort v121, v74, s[26:27]
	s_sub_u32 s26, s26, 0x2200
	s_subb_u32 s27, s27, 0
	global_load_ushort v120, v74, s[26:27]
	s_sub_u32 s26, s26, 0x2200
	s_subb_u32 s27, s27, 0
	global_load_ushort v119, v74, s[26:27]
	s_sub_u32 s26, s26, 0x2200
	s_subb_u32 s27, s27, 0
	global_load_ushort v118, v74, s[26:27]
	s_sub_u32 s26, s26, 0x2200
	s_subb_u32 s27, s27, 0
	global_load_ushort v117, v74, s[26:27]
	s_sub_u32 s26, s26, 0x2200
	s_subb_u32 s27, s27, 0
	global_load_ushort v116, v74, s[26:27]
	s_sub_u32 s26, s26, 0x2200
	s_subb_u32 s27, s27, 0
	global_load_dwordx4 v[132:135], v32, s[28:29] offset:32
	global_load_dwordx4 v[136:139], v32, s[28:29] offset:48
	ds_read_b128 v[92:95], v32 offset:34176
	ds_read_b128 v[96:99], v32 offset:34192
	ds_read_b128 v[100:103], v32 offset:34208
	ds_read_b128 v[104:107], v32 offset:34224
	s_waitcnt lgkmcnt(4)
	v_fma_f32 v152, v76, v12, v48
	v_fmac_f32_e32 v152, v77, v15
	v_fmac_f32_e32 v152, v78, v17
	v_fmac_f32_e32 v152, v79, v19
	v_fmac_f32_e32 v152, v80, v20
	v_fmac_f32_e32 v152, v81, v23
	v_fmac_f32_e32 v152, v82, v25
	v_fmac_f32_e32 v152, v83, v27
	v_fmac_f32_e32 v152, v84, v13
	v_fmac_f32_e32 v152, v85, v14
	v_fmac_f32_e32 v152, v86, v16
	v_fmac_f32_e32 v152, v87, v18
	v_fmac_f32_e32 v152, v88, v21
	v_fmac_f32_e32 v152, v89, v22
	v_fmac_f32_e32 v152, v90, v24
	v_fmac_f32_e32 v152, v91, v26
	v_min_f32_e32 v153, 0, v152
	v_mul_f32_e64 v154, |v152|, s52
	v_exp_f32_e32 v154, v154
	v_mul_f32_e32 v155, 0x3fb8aa3b, v49
	v_add_f32_e32 v154, 1.0, v154
	v_log_f32_e32 v154, v154
	v_exp_f32_e32 v155, v155
	s_waitcnt vmcnt(11)
	v_lshlrev_b32_e32 v156, 16, v115
	v_fmac_f32_e32 v153, 0xbf317218, v154
	v_mul_f32_e32 v157, v155, v156
	v_mul_f32_e32 v147, v131, v157
	v_fmac_f32_e32 v49, 0x3d800000, v153
	ds_read_b128 v[76:79], v32 offset:34112
	ds_read_b128 v[80:83], v32 offset:34128
	ds_read_b128 v[84:87], v32 offset:34144
	ds_read_b128 v[88:91], v32 offset:34160
	s_waitcnt lgkmcnt(4)
	v_fma_f32 v152, v92, v12, v48
	v_fmac_f32_e32 v152, v93, v15
	v_fmac_f32_e32 v152, v94, v17
	v_fmac_f32_e32 v152, v95, v19
	v_fmac_f32_e32 v152, v96, v20
	v_fmac_f32_e32 v152, v97, v23
	v_fmac_f32_e32 v152, v98, v25
	v_fmac_f32_e32 v152, v99, v27
	v_fmac_f32_e32 v152, v100, v13
	v_fmac_f32_e32 v152, v101, v14
	v_fmac_f32_e32 v152, v102, v16
	v_fmac_f32_e32 v152, v103, v18
	v_fmac_f32_e32 v152, v104, v21
	v_fmac_f32_e32 v152, v105, v22
	v_fmac_f32_e32 v152, v106, v24
	v_fmac_f32_e32 v152, v107, v26
	v_min_f32_e32 v153, 0, v152
	v_mul_f32_e64 v154, |v152|, s52
	v_exp_f32_e32 v154, v154
	v_mul_f32_e32 v155, 0x3fb8aa3b, v49
	v_add_f32_e32 v154, 1.0, v154
	v_log_f32_e32 v154, v154
	v_exp_f32_e32 v155, v155
	v_lshlrev_b32_e32 v156, 16, v114
	v_fmac_f32_e32 v153, 0xbf317218, v154
	v_mul_f32_e32 v157, v155, v156
	v_mul_f32_e32 v146, v130, v157
	v_fmac_f32_e32 v49, 0x3d800000, v153
	ds_read_b128 v[92:95], v32 offset:34048
	ds_read_b128 v[96:99], v32 offset:34064
	ds_read_b128 v[100:103], v32 offset:34080
	ds_read_b128 v[104:107], v32 offset:34096
	s_waitcnt lgkmcnt(4)
	v_fma_f32 v152, v76, v12, v48
	v_fmac_f32_e32 v152, v77, v15
	v_fmac_f32_e32 v152, v78, v17
	v_fmac_f32_e32 v152, v79, v19
	v_fmac_f32_e32 v152, v80, v20
	v_fmac_f32_e32 v152, v81, v23
	v_fmac_f32_e32 v152, v82, v25
	v_fmac_f32_e32 v152, v83, v27
	v_fmac_f32_e32 v152, v84, v13
	v_fmac_f32_e32 v152, v85, v14
	v_fmac_f32_e32 v152, v86, v16
	v_fmac_f32_e32 v152, v87, v18
	v_fmac_f32_e32 v152, v88, v21
	v_fmac_f32_e32 v152, v89, v22
	v_fmac_f32_e32 v152, v90, v24
	v_fmac_f32_e32 v152, v91, v26
	v_min_f32_e32 v153, 0, v152
	v_mul_f32_e64 v154, |v152|, s52
	v_exp_f32_e32 v154, v154
	v_mul_f32_e32 v155, 0x3fb8aa3b, v49
	v_add_f32_e32 v154, 1.0, v154
	v_log_f32_e32 v154, v154
	v_exp_f32_e32 v155, v155
	v_lshlrev_b32_e32 v156, 16, v113
	v_fmac_f32_e32 v153, 0xbf317218, v154
	v_mul_f32_e32 v157, v155, v156
	v_mul_f32_e32 v145, v129, v157
	v_fmac_f32_e32 v49, 0x3d800000, v153
	ds_read_b128 v[76:79], v32 offset:33984
	ds_read_b128 v[80:83], v32 offset:34000
	ds_read_b128 v[84:87], v32 offset:34016
	ds_read_b128 v[88:91], v32 offset:34032
	s_waitcnt lgkmcnt(4)
	v_fma_f32 v152, v92, v12, v48
	v_fmac_f32_e32 v152, v93, v15
	v_fmac_f32_e32 v152, v94, v17
	v_fmac_f32_e32 v152, v95, v19
	v_fmac_f32_e32 v152, v96, v20
	v_fmac_f32_e32 v152, v97, v23
	v_fmac_f32_e32 v152, v98, v25
	v_fmac_f32_e32 v152, v99, v27
	v_fmac_f32_e32 v152, v100, v13
	v_fmac_f32_e32 v152, v101, v14
	v_fmac_f32_e32 v152, v102, v16
	v_fmac_f32_e32 v152, v103, v18
	v_fmac_f32_e32 v152, v104, v21
	v_fmac_f32_e32 v152, v105, v22
	v_fmac_f32_e32 v152, v106, v24
	v_fmac_f32_e32 v152, v107, v26
	v_min_f32_e32 v153, 0, v152
	v_mul_f32_e64 v154, |v152|, s52
	v_exp_f32_e32 v154, v154
	v_mul_f32_e32 v155, 0x3fb8aa3b, v49
	v_add_f32_e32 v154, 1.0, v154
	v_log_f32_e32 v154, v154
	v_exp_f32_e32 v155, v155
	v_lshlrev_b32_e32 v156, 16, v112
	v_fmac_f32_e32 v153, 0xbf317218, v154
	v_mul_f32_e32 v157, v155, v156
	v_mul_f32_e32 v144, v128, v157
	v_fmac_f32_e32 v49, 0x3d800000, v153
	ds_read_b128 v[92:95], v32 offset:33920
	ds_read_b128 v[96:99], v32 offset:33936
	ds_read_b128 v[100:103], v32 offset:33952
	ds_read_b128 v[104:107], v32 offset:33968
	s_waitcnt lgkmcnt(4)
	v_fma_f32 v152, v76, v12, v48
	v_fmac_f32_e32 v152, v77, v15
	v_fmac_f32_e32 v152, v78, v17
	v_fmac_f32_e32 v152, v79, v19
	v_fmac_f32_e32 v152, v80, v20
	v_fmac_f32_e32 v152, v81, v23
	v_fmac_f32_e32 v152, v82, v25
	v_fmac_f32_e32 v152, v83, v27
	v_fmac_f32_e32 v152, v84, v13
	v_fmac_f32_e32 v152, v85, v14
	v_fmac_f32_e32 v152, v86, v16
	v_fmac_f32_e32 v152, v87, v18
	v_fmac_f32_e32 v152, v88, v21
	v_fmac_f32_e32 v152, v89, v22
	v_fmac_f32_e32 v152, v90, v24
	v_fmac_f32_e32 v152, v91, v26
	v_min_f32_e32 v153, 0, v152
	v_mul_f32_e64 v154, |v152|, s52
	v_exp_f32_e32 v154, v154
	v_mul_f32_e32 v155, 0x3fb8aa3b, v49
	v_add_f32_e32 v154, 1.0, v154
	v_log_f32_e32 v154, v154
	v_exp_f32_e32 v155, v155
	v_lshlrev_b32_e32 v156, 16, v111
	v_fmac_f32_e32 v153, 0xbf317218, v154
	v_mul_f32_e32 v157, v155, v156
	v_mul_f32_e32 v143, v127, v157
	v_fmac_f32_e32 v49, 0x3d800000, v153
	ds_read_b128 v[76:79], v32 offset:33856
	ds_read_b128 v[80:83], v32 offset:33872
	ds_read_b128 v[84:87], v32 offset:33888
	ds_read_b128 v[88:91], v32 offset:33904
	s_waitcnt lgkmcnt(4)
	v_fma_f32 v152, v92, v12, v48
	v_fmac_f32_e32 v152, v93, v15
	v_fmac_f32_e32 v152, v94, v17
	v_fmac_f32_e32 v152, v95, v19
	v_fmac_f32_e32 v152, v96, v20
	v_fmac_f32_e32 v152, v97, v23
	v_fmac_f32_e32 v152, v98, v25
	v_fmac_f32_e32 v152, v99, v27
	v_fmac_f32_e32 v152, v100, v13
	v_fmac_f32_e32 v152, v101, v14
	v_fmac_f32_e32 v152, v102, v16
	v_fmac_f32_e32 v152, v103, v18
	v_fmac_f32_e32 v152, v104, v21
	v_fmac_f32_e32 v152, v105, v22
	v_fmac_f32_e32 v152, v106, v24
	v_fmac_f32_e32 v152, v107, v26
	v_min_f32_e32 v153, 0, v152
	v_mul_f32_e64 v154, |v152|, s52
	v_exp_f32_e32 v154, v154
	v_mul_f32_e32 v155, 0x3fb8aa3b, v49
	v_add_f32_e32 v154, 1.0, v154
	v_log_f32_e32 v154, v154
	v_exp_f32_e32 v155, v155
	v_lshlrev_b32_e32 v156, 16, v110
	v_fmac_f32_e32 v153, 0xbf317218, v154
	v_mul_f32_e32 v157, v155, v156
	v_mul_f32_e32 v142, v126, v157
	v_fmac_f32_e32 v49, 0x3d800000, v153
	ds_read_b128 v[92:95], v32 offset:33792
	ds_read_b128 v[96:99], v32 offset:33808
	ds_read_b128 v[100:103], v32 offset:33824
	ds_read_b128 v[104:107], v32 offset:33840
	s_waitcnt lgkmcnt(4)
	v_fma_f32 v152, v76, v12, v48
	v_fmac_f32_e32 v152, v77, v15
	v_fmac_f32_e32 v152, v78, v17
	v_fmac_f32_e32 v152, v79, v19
	v_fmac_f32_e32 v152, v80, v20
	v_fmac_f32_e32 v152, v81, v23
	v_fmac_f32_e32 v152, v82, v25
	v_fmac_f32_e32 v152, v83, v27
	v_fmac_f32_e32 v152, v84, v13
	v_fmac_f32_e32 v152, v85, v14
	v_fmac_f32_e32 v152, v86, v16
	v_fmac_f32_e32 v152, v87, v18
	v_fmac_f32_e32 v152, v88, v21
	v_fmac_f32_e32 v152, v89, v22
	v_fmac_f32_e32 v152, v90, v24
	v_fmac_f32_e32 v152, v91, v26
	v_min_f32_e32 v153, 0, v152
	v_mul_f32_e64 v154, |v152|, s52
	v_exp_f32_e32 v154, v154
	v_mul_f32_e32 v155, 0x3fb8aa3b, v49
	v_add_f32_e32 v154, 1.0, v154
	v_log_f32_e32 v154, v154
	v_exp_f32_e32 v155, v155
	v_lshlrev_b32_e32 v156, 16, v109
	v_fmac_f32_e32 v153, 0xbf317218, v154
	v_mul_f32_e32 v157, v155, v156
	v_mul_f32_e32 v141, v125, v157
	v_fmac_f32_e32 v49, 0x3d800000, v153
	ds_read_b128 v[76:79], v32 offset:33728
	ds_read_b128 v[80:83], v32 offset:33744
	ds_read_b128 v[84:87], v32 offset:33760
	ds_read_b128 v[88:91], v32 offset:33776
	s_waitcnt lgkmcnt(4)
	v_fma_f32 v152, v92, v12, v48
	v_fmac_f32_e32 v152, v93, v15
	v_fmac_f32_e32 v152, v94, v17
	v_fmac_f32_e32 v152, v95, v19
	v_fmac_f32_e32 v152, v96, v20
	v_fmac_f32_e32 v152, v97, v23
	v_fmac_f32_e32 v152, v98, v25
	v_fmac_f32_e32 v152, v99, v27
	v_fmac_f32_e32 v152, v100, v13
	v_fmac_f32_e32 v152, v101, v14
	v_fmac_f32_e32 v152, v102, v16
	v_fmac_f32_e32 v152, v103, v18
	v_fmac_f32_e32 v152, v104, v21
	v_fmac_f32_e32 v152, v105, v22
	v_fmac_f32_e32 v152, v106, v24
	v_fmac_f32_e32 v152, v107, v26
	v_min_f32_e32 v153, 0, v152
	v_mul_f32_e64 v154, |v152|, s52
	v_exp_f32_e32 v154, v154
	v_mul_f32_e32 v155, 0x3fb8aa3b, v49
	v_add_f32_e32 v154, 1.0, v154
	v_log_f32_e32 v154, v154
	v_exp_f32_e32 v155, v155
	v_lshlrev_b32_e32 v156, 16, v108
	v_fmac_f32_e32 v153, 0xbf317218, v154
	v_mul_f32_e32 v157, v155, v156
	v_mul_f32_e32 v140, v124, v157
	v_fmac_f32_e32 v49, 0x3d800000, v153
	v_cvt_pk_bf16_f32 v148, v140, v141
	v_cvt_pk_bf16_f32 v149, v142, v143
	v_cvt_pk_bf16_f32 v150, v144, v145
	v_cvt_pk_bf16_f32 v151, v146, v147
	global_store_dwordx4 v[28:29], v[148:151], off offset:32
	global_load_ushort v115, v74, s[26:27]
	s_sub_u32 s26, s26, 0x2200
	s_subb_u32 s27, s27, 0
	global_load_ushort v114, v74, s[26:27]
	s_sub_u32 s26, s26, 0x2200
	s_subb_u32 s27, s27, 0
	global_load_ushort v113, v74, s[26:27]
	s_sub_u32 s26, s26, 0x2200
	s_subb_u32 s27, s27, 0
	global_load_ushort v112, v74, s[26:27]
	s_sub_u32 s26, s26, 0x2200
	s_subb_u32 s27, s27, 0
	global_load_ushort v111, v74, s[26:27]
	s_sub_u32 s26, s26, 0x2200
	s_subb_u32 s27, s27, 0
	global_load_ushort v110, v74, s[26:27]
	s_sub_u32 s26, s26, 0x2200
	s_subb_u32 s27, s27, 0
	global_load_ushort v109, v74, s[26:27]
	s_sub_u32 s26, s26, 0x2200
	s_subb_u32 s27, s27, 0
	global_load_ushort v108, v74, s[26:27]
	s_sub_u32 s26, s26, 0x2200
	s_subb_u32 s27, s27, 0
	global_load_dwordx4 v[124:127], v32, s[28:29] offset:0
	global_load_dwordx4 v[128:131], v32, s[28:29] offset:16
	ds_read_b128 v[92:95], v32 offset:33664
	ds_read_b128 v[96:99], v32 offset:33680
	ds_read_b128 v[100:103], v32 offset:33696
	ds_read_b128 v[104:107], v32 offset:33712
	s_waitcnt lgkmcnt(4)
	v_fma_f32 v152, v76, v12, v48
	v_fmac_f32_e32 v152, v77, v15
	v_fmac_f32_e32 v152, v78, v17
	v_fmac_f32_e32 v152, v79, v19
	v_fmac_f32_e32 v152, v80, v20
	v_fmac_f32_e32 v152, v81, v23
	v_fmac_f32_e32 v152, v82, v25
	v_fmac_f32_e32 v152, v83, v27
	v_fmac_f32_e32 v152, v84, v13
	v_fmac_f32_e32 v152, v85, v14
	v_fmac_f32_e32 v152, v86, v16
	v_fmac_f32_e32 v152, v87, v18
	v_fmac_f32_e32 v152, v88, v21
	v_fmac_f32_e32 v152, v89, v22
	v_fmac_f32_e32 v152, v90, v24
	v_fmac_f32_e32 v152, v91, v26
	v_min_f32_e32 v153, 0, v152
	v_mul_f32_e64 v154, |v152|, s52
	v_exp_f32_e32 v154, v154
	v_mul_f32_e32 v155, 0x3fb8aa3b, v49
	v_add_f32_e32 v154, 1.0, v154
	v_log_f32_e32 v154, v154
	v_exp_f32_e32 v155, v155
	s_waitcnt vmcnt(11)
	v_lshlrev_b32_e32 v156, 16, v123
	v_fmac_f32_e32 v153, 0xbf317218, v154
	v_mul_f32_e32 v157, v155, v156
	v_mul_f32_e32 v147, v139, v157
	v_fmac_f32_e32 v49, 0x3d800000, v153
	ds_read_b128 v[76:79], v32 offset:33600
	ds_read_b128 v[80:83], v32 offset:33616
	ds_read_b128 v[84:87], v32 offset:33632
	ds_read_b128 v[88:91], v32 offset:33648
	s_waitcnt lgkmcnt(4)
	v_fma_f32 v152, v92, v12, v48
	v_fmac_f32_e32 v152, v93, v15
	v_fmac_f32_e32 v152, v94, v17
	v_fmac_f32_e32 v152, v95, v19
	v_fmac_f32_e32 v152, v96, v20
	v_fmac_f32_e32 v152, v97, v23
	v_fmac_f32_e32 v152, v98, v25
	v_fmac_f32_e32 v152, v99, v27
	v_fmac_f32_e32 v152, v100, v13
	v_fmac_f32_e32 v152, v101, v14
	v_fmac_f32_e32 v152, v102, v16
	v_fmac_f32_e32 v152, v103, v18
	v_fmac_f32_e32 v152, v104, v21
	v_fmac_f32_e32 v152, v105, v22
	v_fmac_f32_e32 v152, v106, v24
	v_fmac_f32_e32 v152, v107, v26
	v_min_f32_e32 v153, 0, v152
	v_mul_f32_e64 v154, |v152|, s52
	v_exp_f32_e32 v154, v154
	v_mul_f32_e32 v155, 0x3fb8aa3b, v49
	v_add_f32_e32 v154, 1.0, v154
	v_log_f32_e32 v154, v154
	v_exp_f32_e32 v155, v155
	v_lshlrev_b32_e32 v156, 16, v122
	v_fmac_f32_e32 v153, 0xbf317218, v154
	v_mul_f32_e32 v157, v155, v156
	v_mul_f32_e32 v146, v138, v157
	v_fmac_f32_e32 v49, 0x3d800000, v153
	ds_read_b128 v[92:95], v32 offset:33536
	ds_read_b128 v[96:99], v32 offset:33552
	ds_read_b128 v[100:103], v32 offset:33568
	ds_read_b128 v[104:107], v32 offset:33584
	s_waitcnt lgkmcnt(4)
	v_fma_f32 v152, v76, v12, v48
	v_fmac_f32_e32 v152, v77, v15
	v_fmac_f32_e32 v152, v78, v17
	v_fmac_f32_e32 v152, v79, v19
	v_fmac_f32_e32 v152, v80, v20
	v_fmac_f32_e32 v152, v81, v23
	v_fmac_f32_e32 v152, v82, v25
	v_fmac_f32_e32 v152, v83, v27
	v_fmac_f32_e32 v152, v84, v13
	v_fmac_f32_e32 v152, v85, v14
	v_fmac_f32_e32 v152, v86, v16
	v_fmac_f32_e32 v152, v87, v18
	v_fmac_f32_e32 v152, v88, v21
	v_fmac_f32_e32 v152, v89, v22
	v_fmac_f32_e32 v152, v90, v24
	v_fmac_f32_e32 v152, v91, v26
	v_min_f32_e32 v153, 0, v152
	v_mul_f32_e64 v154, |v152|, s52
	v_exp_f32_e32 v154, v154
	v_mul_f32_e32 v155, 0x3fb8aa3b, v49
	v_add_f32_e32 v154, 1.0, v154
	v_log_f32_e32 v154, v154
	v_exp_f32_e32 v155, v155
	v_lshlrev_b32_e32 v156, 16, v121
	v_fmac_f32_e32 v153, 0xbf317218, v154
	v_mul_f32_e32 v157, v155, v156
	v_mul_f32_e32 v145, v137, v157
	v_fmac_f32_e32 v49, 0x3d800000, v153
	ds_read_b128 v[76:79], v32 offset:33472
	ds_read_b128 v[80:83], v32 offset:33488
	ds_read_b128 v[84:87], v32 offset:33504
	ds_read_b128 v[88:91], v32 offset:33520
	s_waitcnt lgkmcnt(4)
	v_fma_f32 v152, v92, v12, v48
	v_fmac_f32_e32 v152, v93, v15
	v_fmac_f32_e32 v152, v94, v17
	v_fmac_f32_e32 v152, v95, v19
	v_fmac_f32_e32 v152, v96, v20
	v_fmac_f32_e32 v152, v97, v23
	v_fmac_f32_e32 v152, v98, v25
	v_fmac_f32_e32 v152, v99, v27
	v_fmac_f32_e32 v152, v100, v13
	v_fmac_f32_e32 v152, v101, v14
	v_fmac_f32_e32 v152, v102, v16
	v_fmac_f32_e32 v152, v103, v18
	v_fmac_f32_e32 v152, v104, v21
	v_fmac_f32_e32 v152, v105, v22
	v_fmac_f32_e32 v152, v106, v24
	v_fmac_f32_e32 v152, v107, v26
	v_min_f32_e32 v153, 0, v152
	v_mul_f32_e64 v154, |v152|, s52
	v_exp_f32_e32 v154, v154
	v_mul_f32_e32 v155, 0x3fb8aa3b, v49
	v_add_f32_e32 v154, 1.0, v154
	v_log_f32_e32 v154, v154
	v_exp_f32_e32 v155, v155
	v_lshlrev_b32_e32 v156, 16, v120
	v_fmac_f32_e32 v153, 0xbf317218, v154
	v_mul_f32_e32 v157, v155, v156
	v_mul_f32_e32 v144, v136, v157
	v_fmac_f32_e32 v49, 0x3d800000, v153
	ds_read_b128 v[92:95], v32 offset:33408
	ds_read_b128 v[96:99], v32 offset:33424
	ds_read_b128 v[100:103], v32 offset:33440
	ds_read_b128 v[104:107], v32 offset:33456
	s_waitcnt lgkmcnt(4)
	v_fma_f32 v152, v76, v12, v48
	v_fmac_f32_e32 v152, v77, v15
	v_fmac_f32_e32 v152, v78, v17
	v_fmac_f32_e32 v152, v79, v19
	v_fmac_f32_e32 v152, v80, v20
	v_fmac_f32_e32 v152, v81, v23
	v_fmac_f32_e32 v152, v82, v25
	v_fmac_f32_e32 v152, v83, v27
	v_fmac_f32_e32 v152, v84, v13
	v_fmac_f32_e32 v152, v85, v14
	v_fmac_f32_e32 v152, v86, v16
	v_fmac_f32_e32 v152, v87, v18
	v_fmac_f32_e32 v152, v88, v21
	v_fmac_f32_e32 v152, v89, v22
	v_fmac_f32_e32 v152, v90, v24
	v_fmac_f32_e32 v152, v91, v26
	v_min_f32_e32 v153, 0, v152
	v_mul_f32_e64 v154, |v152|, s52
	v_exp_f32_e32 v154, v154
	v_mul_f32_e32 v155, 0x3fb8aa3b, v49
	v_add_f32_e32 v154, 1.0, v154
	v_log_f32_e32 v154, v154
	v_exp_f32_e32 v155, v155
	v_lshlrev_b32_e32 v156, 16, v119
	v_fmac_f32_e32 v153, 0xbf317218, v154
	v_mul_f32_e32 v157, v155, v156
	v_mul_f32_e32 v143, v135, v157
	v_fmac_f32_e32 v49, 0x3d800000, v153
	ds_read_b128 v[76:79], v32 offset:33344
	ds_read_b128 v[80:83], v32 offset:33360
	ds_read_b128 v[84:87], v32 offset:33376
	ds_read_b128 v[88:91], v32 offset:33392
	s_waitcnt lgkmcnt(4)
	v_fma_f32 v152, v92, v12, v48
	v_fmac_f32_e32 v152, v93, v15
	v_fmac_f32_e32 v152, v94, v17
	v_fmac_f32_e32 v152, v95, v19
	v_fmac_f32_e32 v152, v96, v20
	v_fmac_f32_e32 v152, v97, v23
	v_fmac_f32_e32 v152, v98, v25
	v_fmac_f32_e32 v152, v99, v27
	v_fmac_f32_e32 v152, v100, v13
	v_fmac_f32_e32 v152, v101, v14
	v_fmac_f32_e32 v152, v102, v16
	v_fmac_f32_e32 v152, v103, v18
	v_fmac_f32_e32 v152, v104, v21
	v_fmac_f32_e32 v152, v105, v22
	v_fmac_f32_e32 v152, v106, v24
	v_fmac_f32_e32 v152, v107, v26
	v_min_f32_e32 v153, 0, v152
	v_mul_f32_e64 v154, |v152|, s52
	v_exp_f32_e32 v154, v154
	v_mul_f32_e32 v155, 0x3fb8aa3b, v49
	v_add_f32_e32 v154, 1.0, v154
	v_log_f32_e32 v154, v154
	v_exp_f32_e32 v155, v155
	v_lshlrev_b32_e32 v156, 16, v118
	v_fmac_f32_e32 v153, 0xbf317218, v154
	v_mul_f32_e32 v157, v155, v156
	v_mul_f32_e32 v142, v134, v157
	v_fmac_f32_e32 v49, 0x3d800000, v153
	ds_read_b128 v[92:95], v32 offset:33280
	ds_read_b128 v[96:99], v32 offset:33296
	ds_read_b128 v[100:103], v32 offset:33312
	ds_read_b128 v[104:107], v32 offset:33328
	s_waitcnt lgkmcnt(4)
	v_fma_f32 v152, v76, v12, v48
	v_fmac_f32_e32 v152, v77, v15
	v_fmac_f32_e32 v152, v78, v17
	v_fmac_f32_e32 v152, v79, v19
	v_fmac_f32_e32 v152, v80, v20
	v_fmac_f32_e32 v152, v81, v23
	v_fmac_f32_e32 v152, v82, v25
	v_fmac_f32_e32 v152, v83, v27
	v_fmac_f32_e32 v152, v84, v13
	v_fmac_f32_e32 v152, v85, v14
	v_fmac_f32_e32 v152, v86, v16
	v_fmac_f32_e32 v152, v87, v18
	v_fmac_f32_e32 v152, v88, v21
	v_fmac_f32_e32 v152, v89, v22
	v_fmac_f32_e32 v152, v90, v24
	v_fmac_f32_e32 v152, v91, v26
	v_min_f32_e32 v153, 0, v152
	v_mul_f32_e64 v154, |v152|, s52
	v_exp_f32_e32 v154, v154
	v_mul_f32_e32 v155, 0x3fb8aa3b, v49
	v_add_f32_e32 v154, 1.0, v154
	v_log_f32_e32 v154, v154
	v_exp_f32_e32 v155, v155
	v_lshlrev_b32_e32 v156, 16, v117
	v_fmac_f32_e32 v153, 0xbf317218, v154
	v_mul_f32_e32 v157, v155, v156
	v_mul_f32_e32 v141, v133, v157
	v_fmac_f32_e32 v49, 0x3d800000, v153
	ds_read_b128 v[76:79], v32 offset:33216
	ds_read_b128 v[80:83], v32 offset:33232
	ds_read_b128 v[84:87], v32 offset:33248
	ds_read_b128 v[88:91], v32 offset:33264
	s_waitcnt lgkmcnt(4)
	v_fma_f32 v152, v92, v12, v48
	v_fmac_f32_e32 v152, v93, v15
	v_fmac_f32_e32 v152, v94, v17
	v_fmac_f32_e32 v152, v95, v19
	v_fmac_f32_e32 v152, v96, v20
	v_fmac_f32_e32 v152, v97, v23
	v_fmac_f32_e32 v152, v98, v25
	v_fmac_f32_e32 v152, v99, v27
	v_fmac_f32_e32 v152, v100, v13
	v_fmac_f32_e32 v152, v101, v14
	v_fmac_f32_e32 v152, v102, v16
	v_fmac_f32_e32 v152, v103, v18
	v_fmac_f32_e32 v152, v104, v21
	v_fmac_f32_e32 v152, v105, v22
	v_fmac_f32_e32 v152, v106, v24
	v_fmac_f32_e32 v152, v107, v26
	v_min_f32_e32 v153, 0, v152
	v_mul_f32_e64 v154, |v152|, s52
	v_exp_f32_e32 v154, v154
	v_mul_f32_e32 v155, 0x3fb8aa3b, v49
	v_add_f32_e32 v154, 1.0, v154
	v_log_f32_e32 v154, v154
	v_exp_f32_e32 v155, v155
	v_lshlrev_b32_e32 v156, 16, v116
	v_fmac_f32_e32 v153, 0xbf317218, v154
	v_mul_f32_e32 v157, v155, v156
	v_mul_f32_e32 v140, v132, v157
	v_fmac_f32_e32 v49, 0x3d800000, v153
	v_cvt_pk_bf16_f32 v148, v140, v141
	v_cvt_pk_bf16_f32 v149, v142, v143
	v_cvt_pk_bf16_f32 v150, v144, v145
	v_cvt_pk_bf16_f32 v151, v146, v147
	global_store_dwordx4 v[28:29], v[148:151], off offset:16
	ds_read_b128 v[92:95], v32 offset:33152
	ds_read_b128 v[96:99], v32 offset:33168
	ds_read_b128 v[100:103], v32 offset:33184
	ds_read_b128 v[104:107], v32 offset:33200
	s_waitcnt lgkmcnt(4)
	v_fma_f32 v152, v76, v12, v48
	v_fmac_f32_e32 v152, v77, v15
	v_fmac_f32_e32 v152, v78, v17
	v_fmac_f32_e32 v152, v79, v19
	v_fmac_f32_e32 v152, v80, v20
	v_fmac_f32_e32 v152, v81, v23
	v_fmac_f32_e32 v152, v82, v25
	v_fmac_f32_e32 v152, v83, v27
	v_fmac_f32_e32 v152, v84, v13
	v_fmac_f32_e32 v152, v85, v14
	v_fmac_f32_e32 v152, v86, v16
	v_fmac_f32_e32 v152, v87, v18
	v_fmac_f32_e32 v152, v88, v21
	v_fmac_f32_e32 v152, v89, v22
	v_fmac_f32_e32 v152, v90, v24
	v_fmac_f32_e32 v152, v91, v26
	v_min_f32_e32 v153, 0, v152
	v_mul_f32_e64 v154, |v152|, s52
	v_exp_f32_e32 v154, v154
	v_mul_f32_e32 v155, 0x3fb8aa3b, v49
	v_add_f32_e32 v154, 1.0, v154
	v_log_f32_e32 v154, v154
	v_exp_f32_e32 v155, v155
	s_waitcnt vmcnt(1)
	v_lshlrev_b32_e32 v156, 16, v115
	v_fmac_f32_e32 v153, 0xbf317218, v154
	v_mul_f32_e32 v157, v155, v156
	v_mul_f32_e32 v147, v131, v157
	v_fmac_f32_e32 v49, 0x3d800000, v153
	ds_read_b128 v[76:79], v32 offset:33088
	ds_read_b128 v[80:83], v32 offset:33104
	ds_read_b128 v[84:87], v32 offset:33120
	ds_read_b128 v[88:91], v32 offset:33136
	s_waitcnt lgkmcnt(4)
	v_fma_f32 v152, v92, v12, v48
	v_fmac_f32_e32 v152, v93, v15
	v_fmac_f32_e32 v152, v94, v17
	v_fmac_f32_e32 v152, v95, v19
	v_fmac_f32_e32 v152, v96, v20
	v_fmac_f32_e32 v152, v97, v23
	v_fmac_f32_e32 v152, v98, v25
	v_fmac_f32_e32 v152, v99, v27
	v_fmac_f32_e32 v152, v100, v13
	v_fmac_f32_e32 v152, v101, v14
	v_fmac_f32_e32 v152, v102, v16
	v_fmac_f32_e32 v152, v103, v18
	v_fmac_f32_e32 v152, v104, v21
	v_fmac_f32_e32 v152, v105, v22
	v_fmac_f32_e32 v152, v106, v24
	v_fmac_f32_e32 v152, v107, v26
	v_min_f32_e32 v153, 0, v152
	v_mul_f32_e64 v154, |v152|, s52
	v_exp_f32_e32 v154, v154
	v_mul_f32_e32 v155, 0x3fb8aa3b, v49
	v_add_f32_e32 v154, 1.0, v154
	v_log_f32_e32 v154, v154
	v_exp_f32_e32 v155, v155
	v_lshlrev_b32_e32 v156, 16, v114
	v_fmac_f32_e32 v153, 0xbf317218, v154
	v_mul_f32_e32 v157, v155, v156
	v_mul_f32_e32 v146, v130, v157
	v_fmac_f32_e32 v49, 0x3d800000, v153
	ds_read_b128 v[92:95], v32 offset:33024
	ds_read_b128 v[96:99], v32 offset:33040
	ds_read_b128 v[100:103], v32 offset:33056
	ds_read_b128 v[104:107], v32 offset:33072
	s_waitcnt lgkmcnt(4)
	v_fma_f32 v152, v76, v12, v48
	v_fmac_f32_e32 v152, v77, v15
	v_fmac_f32_e32 v152, v78, v17
	v_fmac_f32_e32 v152, v79, v19
	v_fmac_f32_e32 v152, v80, v20
	v_fmac_f32_e32 v152, v81, v23
	v_fmac_f32_e32 v152, v82, v25
	v_fmac_f32_e32 v152, v83, v27
	v_fmac_f32_e32 v152, v84, v13
	v_fmac_f32_e32 v152, v85, v14
	v_fmac_f32_e32 v152, v86, v16
	v_fmac_f32_e32 v152, v87, v18
	v_fmac_f32_e32 v152, v88, v21
	v_fmac_f32_e32 v152, v89, v22
	v_fmac_f32_e32 v152, v90, v24
	v_fmac_f32_e32 v152, v91, v26
	v_min_f32_e32 v153, 0, v152
	v_mul_f32_e64 v154, |v152|, s52
	v_exp_f32_e32 v154, v154
	v_mul_f32_e32 v155, 0x3fb8aa3b, v49
	v_add_f32_e32 v154, 1.0, v154
	v_log_f32_e32 v154, v154
	v_exp_f32_e32 v155, v155
	v_lshlrev_b32_e32 v156, 16, v113
	v_fmac_f32_e32 v153, 0xbf317218, v154
	v_mul_f32_e32 v157, v155, v156
	v_mul_f32_e32 v145, v129, v157
	v_fmac_f32_e32 v49, 0x3d800000, v153
	ds_read_b128 v[76:79], v32 offset:32960
	ds_read_b128 v[80:83], v32 offset:32976
	ds_read_b128 v[84:87], v32 offset:32992
	ds_read_b128 v[88:91], v32 offset:33008
	s_waitcnt lgkmcnt(4)
	v_fma_f32 v152, v92, v12, v48
	v_fmac_f32_e32 v152, v93, v15
	v_fmac_f32_e32 v152, v94, v17
	v_fmac_f32_e32 v152, v95, v19
	v_fmac_f32_e32 v152, v96, v20
	v_fmac_f32_e32 v152, v97, v23
	v_fmac_f32_e32 v152, v98, v25
	v_fmac_f32_e32 v152, v99, v27
	v_fmac_f32_e32 v152, v100, v13
	v_fmac_f32_e32 v152, v101, v14
	v_fmac_f32_e32 v152, v102, v16
	v_fmac_f32_e32 v152, v103, v18
	v_fmac_f32_e32 v152, v104, v21
	v_fmac_f32_e32 v152, v105, v22
	v_fmac_f32_e32 v152, v106, v24
	v_fmac_f32_e32 v152, v107, v26
	v_min_f32_e32 v153, 0, v152
	v_mul_f32_e64 v154, |v152|, s52
	v_exp_f32_e32 v154, v154
	v_mul_f32_e32 v155, 0x3fb8aa3b, v49
	v_add_f32_e32 v154, 1.0, v154
	v_log_f32_e32 v154, v154
	v_exp_f32_e32 v155, v155
	v_lshlrev_b32_e32 v156, 16, v112
	v_fmac_f32_e32 v153, 0xbf317218, v154
	v_mul_f32_e32 v157, v155, v156
	v_mul_f32_e32 v144, v128, v157
	v_fmac_f32_e32 v49, 0x3d800000, v153
	ds_read_b128 v[92:95], v32 offset:32896
	ds_read_b128 v[96:99], v32 offset:32912
	ds_read_b128 v[100:103], v32 offset:32928
	ds_read_b128 v[104:107], v32 offset:32944
	s_waitcnt lgkmcnt(4)
	v_fma_f32 v152, v76, v12, v48
	v_fmac_f32_e32 v152, v77, v15
	v_fmac_f32_e32 v152, v78, v17
	v_fmac_f32_e32 v152, v79, v19
	v_fmac_f32_e32 v152, v80, v20
	v_fmac_f32_e32 v152, v81, v23
	v_fmac_f32_e32 v152, v82, v25
	v_fmac_f32_e32 v152, v83, v27
	v_fmac_f32_e32 v152, v84, v13
	v_fmac_f32_e32 v152, v85, v14
	v_fmac_f32_e32 v152, v86, v16
	v_fmac_f32_e32 v152, v87, v18
	v_fmac_f32_e32 v152, v88, v21
	v_fmac_f32_e32 v152, v89, v22
	v_fmac_f32_e32 v152, v90, v24
	v_fmac_f32_e32 v152, v91, v26
	v_min_f32_e32 v153, 0, v152
	v_mul_f32_e64 v154, |v152|, s52
	v_exp_f32_e32 v154, v154
	v_mul_f32_e32 v155, 0x3fb8aa3b, v49
	v_add_f32_e32 v154, 1.0, v154
	v_log_f32_e32 v154, v154
	v_exp_f32_e32 v155, v155
	v_lshlrev_b32_e32 v156, 16, v111
	v_fmac_f32_e32 v153, 0xbf317218, v154
	v_mul_f32_e32 v157, v155, v156
	v_mul_f32_e32 v143, v127, v157
	v_fmac_f32_e32 v49, 0x3d800000, v153
	ds_read_b128 v[76:79], v32 offset:32832
	ds_read_b128 v[80:83], v32 offset:32848
	ds_read_b128 v[84:87], v32 offset:32864
	ds_read_b128 v[88:91], v32 offset:32880
	s_waitcnt lgkmcnt(4)
	v_fma_f32 v152, v92, v12, v48
	v_fmac_f32_e32 v152, v93, v15
	v_fmac_f32_e32 v152, v94, v17
	v_fmac_f32_e32 v152, v95, v19
	v_fmac_f32_e32 v152, v96, v20
	v_fmac_f32_e32 v152, v97, v23
	v_fmac_f32_e32 v152, v98, v25
	v_fmac_f32_e32 v152, v99, v27
	v_fmac_f32_e32 v152, v100, v13
	v_fmac_f32_e32 v152, v101, v14
	v_fmac_f32_e32 v152, v102, v16
	v_fmac_f32_e32 v152, v103, v18
	v_fmac_f32_e32 v152, v104, v21
	v_fmac_f32_e32 v152, v105, v22
	v_fmac_f32_e32 v152, v106, v24
	v_fmac_f32_e32 v152, v107, v26
	v_min_f32_e32 v153, 0, v152
	v_mul_f32_e64 v154, |v152|, s52
	v_exp_f32_e32 v154, v154
	v_mul_f32_e32 v155, 0x3fb8aa3b, v49
	v_add_f32_e32 v154, 1.0, v154
	v_log_f32_e32 v154, v154
	v_exp_f32_e32 v155, v155
	v_lshlrev_b32_e32 v156, 16, v110
	v_fmac_f32_e32 v153, 0xbf317218, v154
	v_mul_f32_e32 v157, v155, v156
	v_mul_f32_e32 v142, v126, v157
	v_fmac_f32_e32 v49, 0x3d800000, v153
	ds_read_b128 v[92:95], v32 offset:32768
	ds_read_b128 v[96:99], v32 offset:32784
	ds_read_b128 v[100:103], v32 offset:32800
	ds_read_b128 v[104:107], v32 offset:32816
	s_waitcnt lgkmcnt(4)
	v_fma_f32 v152, v76, v12, v48
	v_fmac_f32_e32 v152, v77, v15
	v_fmac_f32_e32 v152, v78, v17
	v_fmac_f32_e32 v152, v79, v19
	v_fmac_f32_e32 v152, v80, v20
	v_fmac_f32_e32 v152, v81, v23
	v_fmac_f32_e32 v152, v82, v25
	v_fmac_f32_e32 v152, v83, v27
	v_fmac_f32_e32 v152, v84, v13
	v_fmac_f32_e32 v152, v85, v14
	v_fmac_f32_e32 v152, v86, v16
	v_fmac_f32_e32 v152, v87, v18
	v_fmac_f32_e32 v152, v88, v21
	v_fmac_f32_e32 v152, v89, v22
	v_fmac_f32_e32 v152, v90, v24
	v_fmac_f32_e32 v152, v91, v26
	v_min_f32_e32 v153, 0, v152
	v_mul_f32_e64 v154, |v152|, s52
	v_exp_f32_e32 v154, v154
	v_mul_f32_e32 v155, 0x3fb8aa3b, v49
	v_add_f32_e32 v154, 1.0, v154
	v_log_f32_e32 v154, v154
	v_exp_f32_e32 v155, v155
	v_lshlrev_b32_e32 v156, 16, v109
	v_fmac_f32_e32 v153, 0xbf317218, v154
	v_mul_f32_e32 v157, v155, v156
	v_mul_f32_e32 v141, v125, v157
	v_fmac_f32_e32 v49, 0x3d800000, v153
	s_waitcnt lgkmcnt(0)
	v_fma_f32 v152, v92, v12, v48
	v_fmac_f32_e32 v152, v93, v15
	v_fmac_f32_e32 v152, v94, v17
	v_fmac_f32_e32 v152, v95, v19
	v_fmac_f32_e32 v152, v96, v20
	v_fmac_f32_e32 v152, v97, v23
	v_fmac_f32_e32 v152, v98, v25
	v_fmac_f32_e32 v152, v99, v27
	v_fmac_f32_e32 v152, v100, v13
	v_fmac_f32_e32 v152, v101, v14
	v_fmac_f32_e32 v152, v102, v16
	v_fmac_f32_e32 v152, v103, v18
	v_fmac_f32_e32 v152, v104, v21
	v_fmac_f32_e32 v152, v105, v22
	v_fmac_f32_e32 v152, v106, v24
	v_fmac_f32_e32 v152, v107, v26
	v_min_f32_e32 v153, 0, v152
	v_mul_f32_e64 v154, |v152|, s52
	v_exp_f32_e32 v154, v154
	v_mul_f32_e32 v155, 0x3fb8aa3b, v49
	v_add_f32_e32 v154, 1.0, v154
	v_log_f32_e32 v154, v154
	v_exp_f32_e32 v155, v155
	v_lshlrev_b32_e32 v156, 16, v108
	v_fmac_f32_e32 v153, 0xbf317218, v154
	v_mul_f32_e32 v157, v155, v156
	v_mul_f32_e32 v140, v124, v157
	v_fmac_f32_e32 v49, 0x3d800000, v153
	v_cvt_pk_bf16_f32 v148, v140, v141
	v_cvt_pk_bf16_f32 v149, v142, v143
	v_cvt_pk_bf16_f32 v150, v144, v145
	v_cvt_pk_bf16_f32 v151, v146, v147
	global_store_dwordx4 v[28:29], v[148:151], off
	s_nop 0
	v_mul_f32_e32 v0, 0x3fb8aa3b, v49
	s_ashr_i32 s39, s38, 31
	v_exp_f32_e32 v2, v0
	s_lshl_b64 s[24:25], s[38:39], 12
	s_add_u32 s24, s22, s24
	v_readlane_b32 s4, v253, 3
	s_addc_u32 s25, s30, s25
	s_add_i32 s41, s41, s4
	s_add_i32 s31, s31, s34
	s_add_i32 s35, s35, s40
	v_lshl_add_u64 v[0:1], v[10:11], 2, s[24:25]
	s_cmpk_gt_i32 s41, 0x1ff
	global_store_dword v[0:1], v2, off
	s_cbranch_scc0 .LBB0_101
	s_mov_b64 s[8:9], s[44:45]
	s_mov_b64 s[16:17], s[48:49]
	s_mov_b64 s[6:7], s[50:51]
	s_mov_b32 s15, s55

.LBB0_151:
	s_cmp_lt_i32 s38, 0
	s_cselect_b64 s[80:81], -1, 0
	s_cmp_gt_i32 s38, -1
	s_cselect_b64 s[0:1], -1, 0
	s_and_b64 vcc, exec, s[80:81]
	s_cbranch_vccnz .LBB0_160
	v_lshl_add_u64 v[112:113], v[106:107], 0, s[2:3]
	s_mov_b32 s2, 3
	v_mov_b32_e32 v109, v203
	v_lshrrev_b32_e32 v205, 4, v165
	v_and_b32_e32 v206, 15, v165
	v_and_b32_e32 v248, 15, v205
	v_xor_b32_e32 v206, v206, v248
	v_lshlrev_b32_e32 v205, 8, v205
	v_lshl_or_b32 v205, v206, 4, v205
	v_add_u32_e32 v205, 0x1ff00, v205
	v_and_b32_e32 v248, 31, v165
	v_bfe_u32 v249, v165, 6, 1
	v_lshl_or_b32 v249, v249, 5, v248
	v_lshlrev_b32_e32 v206, 8, v249
	v_bfe_u32 v249, v165, 1, 3
	v_lshl_or_b32 v206, v249, 5, v206
	v_bfe_u32 v249, v165, 5, 1
	v_xor_b32_e32 v249, v249, v248
	v_and_b32_e32 v249, 1, v249
	v_lshl_or_b32 v206, v249, 4, v206
	v_add_u32_e32 v206, 0x1ff00, v206
	v_xor_b32_e32 v16, 0x20, v206
	v_xor_b32_e32 v17, 0x40, v206
	v_xor_b32_e32 v18, 0x60, v206
	v_xor_b32_e32 v19, 0x80, v206
	v_xor_b32_e32 v20, 0xa0, v206
	v_xor_b32_e32 v21, 0xc0, v206
	v_xor_b32_e32 v22, 0xe0, v206
	v_mov_b32_e32 v207, v109
	s_waitcnt lgkmcnt(0)
	s_cmp_lt_i32 s38, 1
	s_cbranch_scc1 .Lidx_p_w0
	s_waitcnt vmcnt(2)
	s_branch .Lidx_p_w

.Lidx_p_w:
	ds_write_b128 v205, v[88:91]
	ds_write_b128 v205, v[92:95] offset:8192
	s_cmp_lt_i32 s38, 2
	s_cbranch_scc1 .Lidx_p_nopf
	v_add_co_u32_e32 v248, vcc, 0xffffa000, v112
	s_nop 1
	v_addc_co_u32_e32 v249, vcc, -1, v113, vcc
	global_load_dwordx4 v[88:91], v[248:249], off
	v_add_co_u32_e32 v248, vcc, 0xffffc000, v112
	s_nop 1
	v_addc_co_u32_e32 v249, vcc, -1, v113, vcc
	global_load_dwordx4 v[92:95], v[248:249], off
.Lidx_p_nopf:
	s_waitcnt lgkmcnt(0)
	s_barrier
.Lidx_even:
	s_add_i32 s3, s2, -1
	s_add_i32 s24, s2, -2
	s_cmp_gt_i32 s24, s38
	s_cbranch_scc1 .Lidx_e_nost
	s_cmp_gt_i32 s3, s38
	s_cbranch_scc1 .Lidx_e_w0
	s_waitcnt vmcnt(2)
	s_branch .Lidx_e_w

.Lidx_e_w:
	ds_write_b128 v205, v[96:99] offset:16384
	ds_write_b128 v205, v[100:103] offset:24576
.Lidx_e_nost:
	ds_read_b128 v[136:139], v206
	ds_read_b128 v[140:143], v16
	ds_read_b128 v[208:211], v17
	ds_read_b128 v[212:215], v18
	s_cmp_gt_i32 s2, s38
	s_cbranch_scc1 .Lidx_e_nopf
	v_add_co_u32_e32 v248, vcc, 0xffffe000, v112
	s_nop 1
	v_addc_co_u32_e32 v249, vcc, -1, v113, vcc
	global_load_dwordx4 v[96:99], v[248:249], off
	global_load_dwordx4 v[100:103], v[112:113], off
.Lidx_e_nopf:
	s_waitcnt lgkmcnt(3)
	v_mfma_f32_32x32x16_bf16 v[0:15], v[64:67], v[136:139], 0
	ds_read_b128 v[136:139], v19
	v_max_f32_e32 v216, 0, v216
	v_max_f32_e32 v217, 0, v217
	v_fma_f32 v216, v84, v216, 0
	v_max_f32_e32 v218, 0, v218
	s_waitcnt lgkmcnt(3)
	v_mfma_f32_32x32x16_bf16 v[0:15], v[40:43], v[140:143], v[0:15]
	ds_read_b128 v[140:143], v20
	v_fmac_f32_e32 v216, v85, v217
	v_max_f32_e32 v219, 0, v219
	v_fmac_f32_e32 v216, v86, v218
	v_max_f32_e32 v220, 0, v220
	s_waitcnt lgkmcnt(3)
	v_mfma_f32_32x32x16_bf16 v[0:15], v[44:47], v[208:211], v[0:15]
	ds_read_b128 v[208:211], v21
	v_fmac_f32_e32 v216, v87, v219
	v_max_f32_e32 v221, 0, v221
	v_fmac_f32_e32 v216, v80, v220
	v_max_f32_e32 v222, 0, v222
	s_waitcnt lgkmcnt(3)
	v_mfma_f32_32x32x16_bf16 v[0:15], v[48:51], v[212:215], v[0:15]
	ds_read_b128 v[212:215], v22
	v_fmac_f32_e32 v216, v81, v221
	v_max_f32_e32 v223, 0, v223
	v_fmac_f32_e32 v216, v82, v222
	v_max_f32_e32 v224, 0, v224
	s_waitcnt lgkmcnt(3)
	v_mfma_f32_32x32x16_bf16 v[0:15], v[52:55], v[136:139], v[0:15]
	v_fmac_f32_e32 v216, v83, v223
	v_max_f32_e32 v225, 0, v225
	v_fmac_f32_e32 v216, v76, v224
	v_max_f32_e32 v226, 0, v226
	s_waitcnt lgkmcnt(2)
	v_mfma_f32_32x32x16_bf16 v[0:15], v[56:59], v[140:143], v[0:15]
	v_fmac_f32_e32 v216, v77, v225
	v_max_f32_e32 v227, 0, v227
	v_fmac_f32_e32 v216, v78, v226
	v_max_f32_e32 v228, 0, v228
	s_waitcnt lgkmcnt(1)
	v_mfma_f32_32x32x16_bf16 v[0:15], v[60:63], v[208:211], v[0:15]
	v_fmac_f32_e32 v216, v79, v227
	v_max_f32_e32 v229, 0, v229
	v_fmac_f32_e32 v216, v72, v228
	v_max_f32_e32 v230, 0, v230
	s_waitcnt lgkmcnt(0)
	v_mfma_f32_32x32x16_bf16 v[0:15], v[68:71], v[212:215], v[0:15]
	v_fmac_f32_e32 v216, v73, v229
	v_max_f32_e32 v231, 0, v231
	v_fmac_f32_e32 v216, v74, v230
	v_fmac_f32_e32 v216, v75, v231
	ds_write_b32 v207, v216
	s_nop 0
	v_mov_b32_e32 v207, v109
	s_waitcnt lgkmcnt(0)
	s_barrier
	s_add_i32 s24, s2, -2
	s_cmp_gt_i32 s24, s38
	s_cbranch_scc1 .Lidx_exit_e
	s_cmp_gt_i32 s3, s38
	s_cbranch_scc1 .Lidx_o_nost
	s_cmp_gt_i32 s2, s38
	s_cbranch_scc1 .Lidx_o_w0
	s_waitcnt vmcnt(2)
	s_branch .Lidx_o_w

.Lidx_o_w:
	ds_write_b128 v205, v[88:91]
	ds_write_b128 v205, v[92:95] offset:8192
.Lidx_o_nost:
	ds_read_b128 v[136:139], v206 offset:16384
	ds_read_b128 v[140:143], v16 offset:16384
	ds_read_b128 v[208:211], v17 offset:16384
	ds_read_b128 v[212:215], v18 offset:16384
	s_add_i32 s24, s2, 1
	s_cmp_gt_i32 s24, s38
	s_cbranch_scc1 .Lidx_o_nopf
	v_add_co_u32_e32 v248, vcc, 0x2000, v112
	s_nop 1
	v_addc_co_u32_e32 v249, vcc, 0, v113, vcc
	global_load_dwordx4 v[88:91], v[248:249], off
	v_add_co_u32_e32 v248, vcc, 0x4000, v112
	s_nop 1
	v_addc_co_u32_e32 v249, vcc, 0, v113, vcc
	global_load_dwordx4 v[92:95], v[248:249], off
.Lidx_o_nopf:
	s_waitcnt lgkmcnt(3)
	v_mfma_f32_32x32x16_bf16 v[216:231], v[64:67], v[136:139], 0
	ds_read_b128 v[136:139], v19 offset:16384
	v_max_f32_e32 v0, 0, v0
	v_max_f32_e32 v1, 0, v1
	v_fma_f32 v0, v84, v0, 0
	v_max_f32_e32 v2, 0, v2
	s_waitcnt lgkmcnt(3)
	v_mfma_f32_32x32x16_bf16 v[216:231], v[40:43], v[140:143], v[216:231]
	ds_read_b128 v[140:143], v20 offset:16384
	v_fmac_f32_e32 v0, v85, v1
	v_max_f32_e32 v3, 0, v3
	v_fmac_f32_e32 v0, v86, v2
	v_max_f32_e32 v4, 0, v4
	s_waitcnt lgkmcnt(3)
	v_mfma_f32_32x32x16_bf16 v[216:231], v[44:47], v[208:211], v[216:231]
	ds_read_b128 v[208:211], v21 offset:16384
	v_fmac_f32_e32 v0, v87, v3
	v_max_f32_e32 v5, 0, v5
	v_fmac_f32_e32 v0, v80, v4
	v_max_f32_e32 v6, 0, v6
	s_waitcnt lgkmcnt(3)
	v_mfma_f32_32x32x16_bf16 v[216:231], v[48:51], v[212:215], v[216:231]
	ds_read_b128 v[212:215], v22 offset:16384
	v_fmac_f32_e32 v0, v81, v5
	v_max_f32_e32 v7, 0, v7
	v_fmac_f32_e32 v0, v82, v6
	v_max_f32_e32 v8, 0, v8
	s_waitcnt lgkmcnt(3)
	v_mfma_f32_32x32x16_bf16 v[216:231], v[52:55], v[136:139], v[216:231]
	v_fmac_f32_e32 v0, v83, v7
	v_max_f32_e32 v9, 0, v9
	v_fmac_f32_e32 v0, v76, v8
	v_max_f32_e32 v10, 0, v10
	s_waitcnt lgkmcnt(2)
	v_mfma_f32_32x32x16_bf16 v[216:231], v[56:59], v[140:143], v[216:231]
	v_fmac_f32_e32 v0, v77, v9
	v_max_f32_e32 v11, 0, v11
	v_fmac_f32_e32 v0, v78, v10
	v_max_f32_e32 v12, 0, v12
	s_waitcnt lgkmcnt(1)
	v_mfma_f32_32x32x16_bf16 v[216:231], v[60:63], v[208:211], v[216:231]
	v_fmac_f32_e32 v0, v79, v11
	v_max_f32_e32 v13, 0, v13
	v_fmac_f32_e32 v0, v72, v12
	v_max_f32_e32 v14, 0, v14
	s_waitcnt lgkmcnt(0)
	v_mfma_f32_32x32x16_bf16 v[216:231], v[68:71], v[212:215], v[216:231]
	v_fmac_f32_e32 v0, v73, v13
	v_max_f32_e32 v15, 0, v15
	v_fmac_f32_e32 v0, v74, v14
	v_fmac_f32_e32 v0, v75, v15
	ds_write_b32 v207, v0
	s_nop 0
	v_add_u32_e32 v207, 0x100, v109
	s_waitcnt lgkmcnt(0)
	s_barrier
	s_mov_b64 s[24:25], 0x8000
	s_add_i32 s2, s2, 2
	v_lshl_add_u64 v[112:113], v[112:113], 0, s[24:25]
	s_cmp_gt_i32 s3, s38
	v_add_u32_e32 v109, 0x200, v109
	s_cbranch_scc0 .Lidx_even
	s_nop 3
	v_max_f32_e32 v216, 0, v216
	v_max_f32_e32 v217, 0, v217
	v_fma_f32 v216, v84, v216, 0
	v_max_f32_e32 v218, 0, v218
	v_fmac_f32_e32 v216, v85, v217
	v_max_f32_e32 v219, 0, v219
	v_fmac_f32_e32 v216, v86, v218
	v_max_f32_e32 v220, 0, v220
	v_fmac_f32_e32 v216, v87, v219
	v_max_f32_e32 v221, 0, v221
	v_fmac_f32_e32 v216, v80, v220
	v_max_f32_e32 v222, 0, v222
	v_fmac_f32_e32 v216, v81, v221
	v_max_f32_e32 v223, 0, v223
	v_fmac_f32_e32 v216, v82, v222
	v_max_f32_e32 v224, 0, v224
	v_fmac_f32_e32 v216, v83, v223
	v_max_f32_e32 v225, 0, v225
	v_fmac_f32_e32 v216, v76, v224
	v_max_f32_e32 v226, 0, v226
	v_fmac_f32_e32 v216, v77, v225
	v_max_f32_e32 v227, 0, v227
	v_fmac_f32_e32 v216, v78, v226
	v_max_f32_e32 v228, 0, v228
	v_fmac_f32_e32 v216, v79, v227
	v_max_f32_e32 v229, 0, v229
	v_fmac_f32_e32 v216, v72, v228
	v_max_f32_e32 v230, 0, v230
	v_fmac_f32_e32 v216, v73, v229
	v_max_f32_e32 v231, 0, v231
	v_fmac_f32_e32 v216, v74, v230
	v_fmac_f32_e32 v216, v75, v231
	ds_write_b32 v207, v216
	s_branch .LBB0_160
.Lidx_exit_e:
	s_mov_b64 s[24:25], 0x8000
	s_nop 3
	v_max_f32_e32 v0, 0, v0
	v_max_f32_e32 v1, 0, v1
	v_fma_f32 v0, v84, v0, 0
	v_max_f32_e32 v2, 0, v2
	v_fmac_f32_e32 v0, v85, v1
	v_max_f32_e32 v3, 0, v3
	v_fmac_f32_e32 v0, v86, v2
	v_max_f32_e32 v4, 0, v4
	v_fmac_f32_e32 v0, v87, v3
	v_max_f32_e32 v5, 0, v5
	v_fmac_f32_e32 v0, v80, v4
	v_max_f32_e32 v6, 0, v6
	v_fmac_f32_e32 v0, v81, v5
	v_max_f32_e32 v7, 0, v7
	v_fmac_f32_e32 v0, v82, v6
	v_max_f32_e32 v8, 0, v8
	v_fmac_f32_e32 v0, v83, v7
	v_max_f32_e32 v9, 0, v9
	v_fmac_f32_e32 v0, v76, v8
	v_max_f32_e32 v10, 0, v10
	v_fmac_f32_e32 v0, v77, v9
	v_max_f32_e32 v11, 0, v11
	v_fmac_f32_e32 v0, v78, v10
	v_max_f32_e32 v12, 0, v12
	v_fmac_f32_e32 v0, v79, v11
	v_max_f32_e32 v13, 0, v13
	v_fmac_f32_e32 v0, v72, v12
	v_max_f32_e32 v14, 0, v14
	v_fmac_f32_e32 v0, v73, v13
	v_max_f32_e32 v15, 0, v15
	v_fmac_f32_e32 v0, v74, v14
	v_fmac_f32_e32 v0, v75, v15
	ds_write_b32 v207, v0
